# E4g + GEMM K-loops: s_setprio 1 hoisted above the opening barrier and s_setprio 0 sunk below the closing barrier of every MFMA segment
# baseline (speedup 1.0000x reference)
.LBB0_253:
	s_add_i32 s37, s6, 2
	s_add_u32 s58, s4, 0x80
	s_addc_u32 s7, s5, 0
	s_add_i32 s66, 0, 0x10000
	s_cmp_eq_u32 s62, s6
	s_cselect_b32 s7, s55, s7
	s_cselect_b32 s6, s54, s58
	v_add_u32_e32 v112, s66, v188
	s_cselect_b32 s59, s57, s36
	s_cselect_b32 s58, s56, s31
	s_add_i32 s67, 0, 0x14000
	ds_read_b128 v[136:139], v112
	ds_read_b128 v[140:143], v112 offset:1024
	ds_read_b128 v[144:147], v112 offset:2048
	ds_read_b128 v[148:151], v112 offset:3072
	v_add_u32_e32 v112, s67, v188
	ds_read_b128 v[152:155], v112
	ds_read_b128 v[156:159], v112 offset:1024
	ds_read_b128 v[160:163], v112 offset:2048
	ds_read_b128 v[164:167], v112 offset:3072
	v_lshl_add_u64 v[114:115], s[4:5], 0, v[178:179]
	s_add_i32 m0, s28, 0xc000
	ds_read_b128 v[192:195], v190
	ds_read_b128 v[196:199], v190 offset:1024
	ds_read_b128 v[200:203], v190 offset:2048
	ds_read_b128 v[208:211], v190 offset:3072
	ds_read_b128 v[212:215], v190 offset:4096
	ds_read_b128 v[216:219], v190 offset:5120
	ds_read_b128 v[220:223], v190 offset:6144
	ds_read_b128 v[224:227], v190 offset:7168
	global_load_lds_dwordx4 v[114:115], off
	v_lshl_add_u64 v[114:115], s[4:5], 0, v[180:181]
	s_add_i32 m0, s28, 0xe000
	s_nop 0
	global_load_lds_dwordx4 v[114:115], off
	s_waitcnt vmcnt(8)
	s_waitcnt lgkmcnt(0)
	s_setprio 1
	s_barrier
	s_waitcnt lgkmcnt(0)
	v_mfma_f32_16x16x32_bf16 v[132:135], v[136:139], v[192:195], v[132:135]
	v_mfma_f32_16x16x32_bf16 v[128:131], v[144:147], v[192:195], v[128:131]
	v_mfma_f32_16x16x32_bf16 v[114:117], v[136:139], v[200:203], v[116:119]
	v_mfma_f32_16x16x32_bf16 v[106:109], v[144:147], v[200:203], v[106:109]
	v_mfma_f32_16x16x32_bf16 v[94:97], v[136:139], v[212:215], v[94:97]
	v_mfma_f32_16x16x32_bf16 v[90:93], v[144:147], v[212:215], v[90:93]
	v_mfma_f32_16x16x32_bf16 v[78:81], v[136:139], v[220:223], v[78:81]
	v_mfma_f32_16x16x32_bf16 v[74:77], v[144:147], v[220:223], v[74:77]
	v_mfma_f32_16x16x32_bf16 v[132:135], v[140:143], v[196:199], v[132:135]
	v_mfma_f32_16x16x32_bf16 v[128:131], v[148:151], v[196:199], v[128:131]
	v_mfma_f32_16x16x32_bf16 v[114:117], v[140:143], v[208:211], v[114:117]
	v_mfma_f32_16x16x32_bf16 v[106:109], v[148:151], v[208:211], v[106:109]
	v_mfma_f32_16x16x32_bf16 v[94:97], v[140:143], v[216:219], v[94:97]
	v_mfma_f32_16x16x32_bf16 v[90:93], v[148:151], v[216:219], v[90:93]
	v_mfma_f32_16x16x32_bf16 v[78:81], v[140:143], v[224:227], v[78:81]
	v_mfma_f32_16x16x32_bf16 v[74:77], v[148:151], v[224:227], v[74:77]
	v_mfma_f32_16x16x32_bf16 v[124:127], v[152:155], v[192:195], v[124:127]
	v_mfma_f32_16x16x32_bf16 v[118:121], v[160:163], v[192:195], v[120:123]
	v_mfma_f32_16x16x32_bf16 v[102:105], v[152:155], v[200:203], v[102:105]
	v_mfma_f32_16x16x32_bf16 v[98:101], v[160:163], v[200:203], v[98:101]
	v_mfma_f32_16x16x32_bf16 v[86:89], v[152:155], v[212:215], v[86:89]
	v_mfma_f32_16x16x32_bf16 v[82:85], v[160:163], v[212:215], v[82:85]
	v_mfma_f32_16x16x32_bf16 v[70:73], v[152:155], v[220:223], v[70:73]
	v_mfma_f32_16x16x32_bf16 v[66:69], v[160:163], v[220:223], v[66:69]
	v_mfma_f32_16x16x32_bf16 v[124:127], v[156:159], v[196:199], v[124:127]
	v_mfma_f32_16x16x32_bf16 v[120:123], v[164:167], v[196:199], v[118:121]
	v_mfma_f32_16x16x32_bf16 v[102:105], v[156:159], v[208:211], v[102:105]
	v_mfma_f32_16x16x32_bf16 v[98:101], v[164:167], v[208:211], v[98:101]
	v_mfma_f32_16x16x32_bf16 v[86:89], v[156:159], v[216:219], v[86:89]
	v_mfma_f32_16x16x32_bf16 v[82:85], v[164:167], v[216:219], v[82:85]
	v_mfma_f32_16x16x32_bf16 v[70:73], v[156:159], v[224:227], v[70:73]
	v_mfma_f32_16x16x32_bf16 v[66:69], v[164:167], v[224:227], v[66:69]
	s_barrier
	s_setprio 0
	s_add_i32 s66, s66, s27
	v_lshl_add_u64 v[204:205], s[58:59], 0, v[174:175]
	s_mov_b32 m0, s66
	ds_read_b128 v[192:195], v190 offset:16384
	ds_read_b128 v[196:199], v190 offset:17408
	ds_read_b128 v[200:203], v190 offset:18432
	ds_read_b128 v[208:211], v190 offset:19456
	ds_read_b128 v[212:215], v190 offset:20480
	ds_read_b128 v[216:219], v190 offset:21504
	ds_read_b128 v[220:223], v190 offset:22528
	ds_read_b128 v[224:227], v190 offset:23552
	global_load_lds_dwordx4 v[204:205], off
	s_add_i32 m0, s66, 0x2000
	v_lshl_add_u64 v[228:229], s[58:59], 0, v[110:111]
	s_add_u32 s58, s58, s10
	s_addc_u32 s59, s59, s11
	s_add_i32 s66, s67, s27
	global_load_lds_dwordx4 v[228:229], off
	v_lshl_add_u64 v[230:231], s[58:59], 0, v[174:175]
	s_mov_b32 m0, s66
	v_lshl_add_u64 v[232:233], s[58:59], 0, v[110:111]
	global_load_lds_dwordx4 v[230:231], off
	s_add_i32 m0, s66, 0x2000
	v_lshl_add_u64 v[234:235], s[6:7], 0, v[176:177]
	global_load_lds_dwordx4 v[232:233], off
	s_mov_b32 m0, s28
	v_lshl_add_u64 v[236:237], s[6:7], 0, v[172:173]
	global_load_lds_dwordx4 v[234:235], off
	s_mov_b32 m0, s29
	s_nop 0
	global_load_lds_dwordx4 v[236:237], off
	s_waitcnt vmcnt(8)
	s_waitcnt lgkmcnt(0)
	s_setprio 1
	s_barrier
	s_waitcnt lgkmcnt(0)
	v_mfma_f32_16x16x32_bf16 v[62:65], v[136:139], v[192:195], v[62:65]
	v_mfma_f32_16x16x32_bf16 v[58:61], v[144:147], v[192:195], v[58:61]
	v_mfma_f32_16x16x32_bf16 v[46:49], v[136:139], v[200:203], v[46:49]
	v_mfma_f32_16x16x32_bf16 v[42:45], v[144:147], v[200:203], v[42:45]
	v_mfma_f32_16x16x32_bf16 v[30:33], v[136:139], v[212:215], v[30:33]
	v_mfma_f32_16x16x32_bf16 v[26:29], v[144:147], v[212:215], v[26:29]
	v_mfma_f32_16x16x32_bf16 v[14:17], v[136:139], v[220:223], v[14:17]
	v_mfma_f32_16x16x32_bf16 v[10:13], v[144:147], v[220:223], v[10:13]
	v_mfma_f32_16x16x32_bf16 v[62:65], v[140:143], v[196:199], v[62:65]
	v_mfma_f32_16x16x32_bf16 v[58:61], v[148:151], v[196:199], v[58:61]
	v_mfma_f32_16x16x32_bf16 v[46:49], v[140:143], v[208:211], v[46:49]
	v_mfma_f32_16x16x32_bf16 v[42:45], v[148:151], v[208:211], v[42:45]
	v_mfma_f32_16x16x32_bf16 v[30:33], v[140:143], v[216:219], v[30:33]
	v_mfma_f32_16x16x32_bf16 v[26:29], v[148:151], v[216:219], v[26:29]
	v_mfma_f32_16x16x32_bf16 v[14:17], v[140:143], v[224:227], v[14:17]
	v_mfma_f32_16x16x32_bf16 v[10:13], v[148:151], v[224:227], v[10:13]
	v_mfma_f32_16x16x32_bf16 v[54:57], v[152:155], v[192:195], v[54:57]
	v_mfma_f32_16x16x32_bf16 v[50:53], v[160:163], v[192:195], v[50:53]
	v_mfma_f32_16x16x32_bf16 v[38:41], v[152:155], v[200:203], v[38:41]
	v_mfma_f32_16x16x32_bf16 v[34:37], v[160:163], v[200:203], v[34:37]
	v_mfma_f32_16x16x32_bf16 v[22:25], v[152:155], v[212:215], v[22:25]
	v_mfma_f32_16x16x32_bf16 v[18:21], v[160:163], v[212:215], v[18:21]
	v_mfma_f32_16x16x32_bf16 v[6:9], v[152:155], v[220:223], v[6:9]
	v_mfma_f32_16x16x32_bf16 v[2:5], v[160:163], v[220:223], v[2:5]
	v_mfma_f32_16x16x32_bf16 v[54:57], v[156:159], v[196:199], v[54:57]
	v_mfma_f32_16x16x32_bf16 v[50:53], v[164:167], v[196:199], v[50:53]
	v_mfma_f32_16x16x32_bf16 v[38:41], v[156:159], v[208:211], v[38:41]
	v_mfma_f32_16x16x32_bf16 v[34:37], v[164:167], v[208:211], v[34:37]
	v_mfma_f32_16x16x32_bf16 v[22:25], v[156:159], v[216:219], v[22:25]
	v_mfma_f32_16x16x32_bf16 v[18:21], v[164:167], v[216:219], v[18:21]
	v_mfma_f32_16x16x32_bf16 v[6:9], v[156:159], v[224:227], v[6:9]
	v_mfma_f32_16x16x32_bf16 v[2:5], v[164:167], v[224:227], v[2:5]
	s_barrier
	s_setprio 0
	s_add_i32 s58, 0, 0x18000
	v_add_u32_e32 v112, s58, v188
	s_add_i32 s59, 0, 0x1c000
	ds_read_b128 v[136:139], v112
	ds_read_b128 v[140:143], v112 offset:1024
	ds_read_b128 v[144:147], v112 offset:2048
	ds_read_b128 v[148:151], v112 offset:3072
	v_add_u32_e32 v112, s59, v188
	ds_read_b128 v[152:155], v112
	ds_read_b128 v[156:159], v112 offset:1024
	ds_read_b128 v[160:163], v112 offset:2048
	ds_read_b128 v[164:167], v112 offset:3072
	s_add_u32 s6, s6, s10
	s_addc_u32 s7, s7, s11
	s_mov_b32 m0, s34
	v_lshl_add_u64 v[118:119], s[6:7], 0, v[176:177]
	ds_read_b128 v[192:195], v190 offset:32768
	ds_read_b128 v[196:199], v190 offset:33792
	ds_read_b128 v[200:203], v190 offset:34816
	ds_read_b128 v[208:211], v190 offset:35840
	ds_read_b128 v[212:215], v190 offset:36864
	ds_read_b128 v[216:219], v190 offset:37888
	ds_read_b128 v[220:223], v190 offset:38912
	ds_read_b128 v[224:227], v190 offset:39936
	global_load_lds_dwordx4 v[118:119], off
	v_lshl_add_u64 v[118:119], s[6:7], 0, v[172:173]
	s_mov_b32 m0, s44
	s_nop 0
	global_load_lds_dwordx4 v[118:119], off
	s_waitcnt vmcnt(8)
	s_waitcnt lgkmcnt(0)
	s_setprio 1
	s_barrier
	s_waitcnt lgkmcnt(0)
	v_mfma_f32_16x16x32_bf16 v[132:135], v[136:139], v[192:195], v[132:135]
	v_mfma_f32_16x16x32_bf16 v[128:131], v[144:147], v[192:195], v[128:131]
	v_mfma_f32_16x16x32_bf16 v[114:117], v[136:139], v[200:203], v[114:117]
	v_mfma_f32_16x16x32_bf16 v[106:109], v[144:147], v[200:203], v[106:109]
	v_mfma_f32_16x16x32_bf16 v[94:97], v[136:139], v[212:215], v[94:97]
	v_mfma_f32_16x16x32_bf16 v[90:93], v[144:147], v[212:215], v[90:93]
	v_mfma_f32_16x16x32_bf16 v[78:81], v[136:139], v[220:223], v[78:81]
	v_mfma_f32_16x16x32_bf16 v[74:77], v[144:147], v[220:223], v[74:77]
	v_mfma_f32_16x16x32_bf16 v[132:135], v[140:143], v[196:199], v[132:135]
	v_mfma_f32_16x16x32_bf16 v[128:131], v[148:151], v[196:199], v[128:131]
	v_mfma_f32_16x16x32_bf16 v[116:119], v[140:143], v[208:211], v[114:117]
	v_mfma_f32_16x16x32_bf16 v[106:109], v[148:151], v[208:211], v[106:109]
	v_mfma_f32_16x16x32_bf16 v[94:97], v[140:143], v[216:219], v[94:97]
	v_mfma_f32_16x16x32_bf16 v[90:93], v[148:151], v[216:219], v[90:93]
	v_mfma_f32_16x16x32_bf16 v[78:81], v[140:143], v[224:227], v[78:81]
	v_mfma_f32_16x16x32_bf16 v[74:77], v[148:151], v[224:227], v[74:77]
	v_mfma_f32_16x16x32_bf16 v[124:127], v[152:155], v[192:195], v[124:127]
	v_mfma_f32_16x16x32_bf16 v[120:123], v[160:163], v[192:195], v[120:123]
	v_mfma_f32_16x16x32_bf16 v[102:105], v[152:155], v[200:203], v[102:105]
	v_mfma_f32_16x16x32_bf16 v[98:101], v[160:163], v[200:203], v[98:101]
	v_mfma_f32_16x16x32_bf16 v[86:89], v[152:155], v[212:215], v[86:89]
	v_mfma_f32_16x16x32_bf16 v[82:85], v[160:163], v[212:215], v[82:85]
	v_mfma_f32_16x16x32_bf16 v[70:73], v[152:155], v[220:223], v[70:73]
	v_mfma_f32_16x16x32_bf16 v[66:69], v[160:163], v[220:223], v[66:69]
	v_mfma_f32_16x16x32_bf16 v[124:127], v[156:159], v[196:199], v[124:127]
	v_mfma_f32_16x16x32_bf16 v[120:123], v[164:167], v[196:199], v[120:123]
	v_mfma_f32_16x16x32_bf16 v[102:105], v[156:159], v[208:211], v[102:105]
	v_mfma_f32_16x16x32_bf16 v[98:101], v[164:167], v[208:211], v[98:101]
	v_mfma_f32_16x16x32_bf16 v[86:89], v[156:159], v[216:219], v[86:89]
	v_mfma_f32_16x16x32_bf16 v[82:85], v[164:167], v[216:219], v[82:85]
	v_mfma_f32_16x16x32_bf16 v[70:73], v[156:159], v[224:227], v[70:73]
	v_mfma_f32_16x16x32_bf16 v[66:69], v[164:167], v[224:227], v[66:69]
	s_barrier
	s_setprio 0
	s_add_i32 s6, s58, s27
	v_lshl_add_u64 v[114:115], v[204:205], 0, s[38:39]
	s_mov_b32 m0, s6
	ds_read_b128 v[192:195], v190 offset:49152
	ds_read_b128 v[196:199], v190 offset:50176
	ds_read_b128 v[200:203], v190 offset:51200
	ds_read_b128 v[208:211], v190 offset:52224
	ds_read_b128 v[212:215], v190 offset:53248
	ds_read_b128 v[216:219], v190 offset:54272
	ds_read_b128 v[220:223], v190 offset:55296
	ds_read_b128 v[224:227], v190 offset:56320
	global_load_lds_dwordx4 v[114:115], off
	v_lshl_add_u64 v[114:115], v[228:229], 0, s[38:39]
	s_add_i32 m0, s6, 0x2000
	s_add_i32 s6, s59, s27
	global_load_lds_dwordx4 v[114:115], off
	v_lshl_add_u64 v[114:115], v[230:231], 0, s[38:39]
	s_mov_b32 m0, s6
	s_nop 0
	global_load_lds_dwordx4 v[114:115], off
	v_lshl_add_u64 v[114:115], v[232:233], 0, s[38:39]
	s_add_i32 m0, s6, 0x2000
	s_nop 0
	global_load_lds_dwordx4 v[114:115], off
	v_lshl_add_u64 v[114:115], v[234:235], 0, s[38:39]
	s_mov_b32 m0, s45
	s_nop 0
	global_load_lds_dwordx4 v[114:115], off
	v_lshl_add_u64 v[114:115], v[236:237], 0, s[38:39]
	s_mov_b32 m0, s60
	s_nop 0
	global_load_lds_dwordx4 v[114:115], off
	s_waitcnt vmcnt(8)
	s_waitcnt lgkmcnt(0)
	s_setprio 1
	s_barrier
	s_waitcnt lgkmcnt(0)
	v_mfma_f32_16x16x32_bf16 v[62:65], v[136:139], v[192:195], v[62:65]
	v_mfma_f32_16x16x32_bf16 v[58:61], v[144:147], v[192:195], v[58:61]
	v_mfma_f32_16x16x32_bf16 v[46:49], v[136:139], v[200:203], v[46:49]
	v_mfma_f32_16x16x32_bf16 v[42:45], v[144:147], v[200:203], v[42:45]
	v_mfma_f32_16x16x32_bf16 v[30:33], v[136:139], v[212:215], v[30:33]
	v_mfma_f32_16x16x32_bf16 v[26:29], v[144:147], v[212:215], v[26:29]
	v_mfma_f32_16x16x32_bf16 v[14:17], v[136:139], v[220:223], v[14:17]
	v_mfma_f32_16x16x32_bf16 v[10:13], v[144:147], v[220:223], v[10:13]
	v_mfma_f32_16x16x32_bf16 v[62:65], v[140:143], v[196:199], v[62:65]
	v_mfma_f32_16x16x32_bf16 v[58:61], v[148:151], v[196:199], v[58:61]
	v_mfma_f32_16x16x32_bf16 v[46:49], v[140:143], v[208:211], v[46:49]
	v_mfma_f32_16x16x32_bf16 v[42:45], v[148:151], v[208:211], v[42:45]
	v_mfma_f32_16x16x32_bf16 v[30:33], v[140:143], v[216:219], v[30:33]
	v_mfma_f32_16x16x32_bf16 v[26:29], v[148:151], v[216:219], v[26:29]
	v_mfma_f32_16x16x32_bf16 v[14:17], v[140:143], v[224:227], v[14:17]
	v_mfma_f32_16x16x32_bf16 v[10:13], v[148:151], v[224:227], v[10:13]
	v_mfma_f32_16x16x32_bf16 v[54:57], v[152:155], v[192:195], v[54:57]
	v_mfma_f32_16x16x32_bf16 v[50:53], v[160:163], v[192:195], v[50:53]
	v_mfma_f32_16x16x32_bf16 v[38:41], v[152:155], v[200:203], v[38:41]
	v_mfma_f32_16x16x32_bf16 v[34:37], v[160:163], v[200:203], v[34:37]
	v_mfma_f32_16x16x32_bf16 v[22:25], v[152:155], v[212:215], v[22:25]
	v_mfma_f32_16x16x32_bf16 v[18:21], v[160:163], v[212:215], v[18:21]
	v_mfma_f32_16x16x32_bf16 v[6:9], v[152:155], v[220:223], v[6:9]
	v_mfma_f32_16x16x32_bf16 v[2:5], v[160:163], v[220:223], v[2:5]
	v_mfma_f32_16x16x32_bf16 v[54:57], v[156:159], v[196:199], v[54:57]
	v_mfma_f32_16x16x32_bf16 v[50:53], v[164:167], v[196:199], v[50:53]
	v_mfma_f32_16x16x32_bf16 v[38:41], v[156:159], v[208:211], v[38:41]
	v_mfma_f32_16x16x32_bf16 v[34:37], v[164:167], v[208:211], v[34:37]
	v_mfma_f32_16x16x32_bf16 v[22:25], v[156:159], v[216:219], v[22:25]
	v_mfma_f32_16x16x32_bf16 v[18:21], v[164:167], v[216:219], v[18:21]
	v_mfma_f32_16x16x32_bf16 v[6:9], v[156:159], v[224:227], v[6:9]
	v_mfma_f32_16x16x32_bf16 v[2:5], v[164:167], v[224:227], v[2:5]
	s_barrier
	s_setprio 0
	s_add_u32 s4, s4, 0x100
	s_addc_u32 s5, s5, 0
	s_add_u32 s31, s31, 0x100
	s_addc_u32 s36, s36, 0
	s_cmp_ge_i32 s37, s61
	s_mov_b32 s6, s37
	s_cbranch_scc0 .LBB0_253

.LBB0_529:
	ds_read_b128 v[128:131], v210
	ds_read_b128 v[132:135], v210 offset:1024
	ds_read_b128 v[136:139], v210 offset:2048
	ds_read_b128 v[140:143], v210 offset:3072
	ds_read_b128 v[144:147], v211
	ds_read_b128 v[148:151], v211 offset:1024
	ds_read_b128 v[152:155], v211 offset:2048
	ds_read_b128 v[156:159], v211 offset:3072
	s_add_i32 s65, s54, 2
	s_add_u32 s66, s52, 0x80
	s_addc_u32 s55, s53, 0
	s_cmp_eq_u32 s59, s54
	s_cselect_b32 s54, s10, s66
	s_cselect_b32 s55, s11, s55
	s_cselect_b32 s67, s51, s64
	s_cselect_b32 s66, s50, s16
	v_lshl_add_u64 v[218:219], s[52:53], 0, v[186:187]
	s_add_i32 m0, s25, 0xc000
	ds_read_b128 v[160:163], v212
	ds_read_b128 v[164:167], v212 offset:1024
	ds_read_b128 v[168:171], v212 offset:2048
	ds_read_b128 v[172:175], v212 offset:3072
	ds_read_b128 v[194:197], v212 offset:4096
	ds_read_b128 v[198:201], v212 offset:5120
	ds_read_b128 v[202:205], v212 offset:6144
	ds_read_b128 v[214:217], v212 offset:7168
	global_load_lds_dwordx4 v[218:219], off
	v_lshl_add_u64 v[218:219], s[52:53], 0, v[188:189]
	s_add_i32 m0, s25, 0xe000
	s_nop 0
	global_load_lds_dwordx4 v[218:219], off
	s_waitcnt vmcnt(8)
	s_waitcnt lgkmcnt(0)
	s_setprio 1
	s_barrier
	s_waitcnt lgkmcnt(0)
	v_mfma_f32_16x16x32_bf16 v[120:123], v[128:131], v[160:163], v[120:123]
	v_mfma_f32_16x16x32_bf16 v[124:127], v[136:139], v[160:163], v[124:127]
	v_mfma_f32_16x16x32_bf16 v[108:111], v[128:131], v[168:171], v[108:111]
	v_mfma_f32_16x16x32_bf16 v[104:107], v[136:139], v[168:171], v[104:107]
	v_mfma_f32_16x16x32_bf16 v[92:95], v[128:131], v[194:197], v[92:95]
	v_mfma_f32_16x16x32_bf16 v[88:91], v[136:139], v[194:197], v[88:91]
	v_mfma_f32_16x16x32_bf16 v[76:79], v[128:131], v[202:205], v[76:79]
	v_mfma_f32_16x16x32_bf16 v[72:75], v[136:139], v[202:205], v[72:75]
	v_mfma_f32_16x16x32_bf16 v[120:123], v[132:135], v[164:167], v[120:123]
	v_mfma_f32_16x16x32_bf16 v[124:127], v[140:143], v[164:167], v[124:127]
	v_mfma_f32_16x16x32_bf16 v[108:111], v[132:135], v[172:175], v[108:111]
	v_mfma_f32_16x16x32_bf16 v[104:107], v[140:143], v[172:175], v[104:107]
	v_mfma_f32_16x16x32_bf16 v[92:95], v[132:135], v[198:201], v[92:95]
	v_mfma_f32_16x16x32_bf16 v[88:91], v[140:143], v[198:201], v[88:91]
	v_mfma_f32_16x16x32_bf16 v[76:79], v[132:135], v[214:217], v[76:79]
	v_mfma_f32_16x16x32_bf16 v[72:75], v[140:143], v[214:217], v[72:75]
	v_mfma_f32_16x16x32_bf16 v[116:119], v[144:147], v[160:163], v[116:119]
	v_mfma_f32_16x16x32_bf16 v[112:115], v[152:155], v[160:163], v[112:115]
	v_mfma_f32_16x16x32_bf16 v[100:103], v[144:147], v[168:171], v[100:103]
	v_mfma_f32_16x16x32_bf16 v[96:99], v[152:155], v[168:171], v[96:99]
	v_mfma_f32_16x16x32_bf16 v[84:87], v[144:147], v[194:197], v[84:87]
	v_mfma_f32_16x16x32_bf16 v[80:83], v[152:155], v[194:197], v[80:83]
	v_mfma_f32_16x16x32_bf16 v[68:71], v[144:147], v[202:205], v[68:71]
	v_mfma_f32_16x16x32_bf16 v[64:67], v[152:155], v[202:205], v[64:67]
	v_mfma_f32_16x16x32_bf16 v[116:119], v[148:151], v[164:167], v[116:119]
	v_mfma_f32_16x16x32_bf16 v[112:115], v[156:159], v[164:167], v[112:115]
	v_mfma_f32_16x16x32_bf16 v[100:103], v[148:151], v[172:175], v[100:103]
	v_mfma_f32_16x16x32_bf16 v[96:99], v[156:159], v[172:175], v[96:99]
	v_mfma_f32_16x16x32_bf16 v[84:87], v[148:151], v[198:201], v[84:87]
	v_mfma_f32_16x16x32_bf16 v[80:83], v[156:159], v[198:201], v[80:83]
	v_mfma_f32_16x16x32_bf16 v[68:71], v[148:151], v[214:217], v[68:71]
	v_mfma_f32_16x16x32_bf16 v[64:67], v[156:159], v[214:217], v[64:67]
	s_barrier
	s_setprio 0
	s_add_i32 s68, s60, s24
	v_lshl_add_u64 v[218:219], s[66:67], 0, v[178:179]
	s_mov_b32 m0, s68
	ds_read_b128 v[160:163], v212 offset:16384
	ds_read_b128 v[164:167], v212 offset:17408
	ds_read_b128 v[168:171], v212 offset:18432
	ds_read_b128 v[172:175], v212 offset:19456
	ds_read_b128 v[194:197], v212 offset:20480
	ds_read_b128 v[198:201], v212 offset:21504
	ds_read_b128 v[202:205], v212 offset:22528
	ds_read_b128 v[214:217], v212 offset:23552
	global_load_lds_dwordx4 v[218:219], off
	s_add_i32 m0, s68, 0x2000
	v_lshl_add_u64 v[220:221], s[66:67], 0, v[182:183]
	s_add_u32 s66, s66, s28
	s_addc_u32 s67, s67, s29
	s_add_i32 s68, s61, s24
	global_load_lds_dwordx4 v[220:221], off
	v_lshl_add_u64 v[222:223], s[66:67], 0, v[178:179]
	s_mov_b32 m0, s68
	v_lshl_add_u64 v[224:225], s[66:67], 0, v[182:183]
	global_load_lds_dwordx4 v[222:223], off
	s_add_i32 m0, s68, 0x2000
	v_lshl_add_u64 v[226:227], s[54:55], 0, v[176:177]
	global_load_lds_dwordx4 v[224:225], off
	s_mov_b32 m0, s25
	v_lshl_add_u64 v[228:229], s[54:55], 0, v[180:181]
	global_load_lds_dwordx4 v[226:227], off
	s_mov_b32 m0, s26
	s_nop 0
	global_load_lds_dwordx4 v[228:229], off
	s_waitcnt vmcnt(8)
	s_waitcnt lgkmcnt(0)
	s_setprio 1
	s_barrier
	s_waitcnt lgkmcnt(0)
	v_mfma_f32_16x16x32_bf16 v[60:63], v[128:131], v[160:163], v[60:63]
	v_mfma_f32_16x16x32_bf16 v[56:59], v[136:139], v[160:163], v[56:59]
	v_mfma_f32_16x16x32_bf16 v[44:47], v[128:131], v[168:171], v[44:47]
	v_mfma_f32_16x16x32_bf16 v[40:43], v[136:139], v[168:171], v[40:43]
	v_mfma_f32_16x16x32_bf16 v[28:31], v[128:131], v[194:197], v[28:31]
	v_mfma_f32_16x16x32_bf16 v[24:27], v[136:139], v[194:197], v[24:27]
	v_mfma_f32_16x16x32_bf16 v[12:15], v[128:131], v[202:205], v[12:15]
	v_mfma_f32_16x16x32_bf16 v[8:11], v[136:139], v[202:205], v[8:11]
	v_mfma_f32_16x16x32_bf16 v[60:63], v[132:135], v[164:167], v[60:63]
	v_mfma_f32_16x16x32_bf16 v[56:59], v[140:143], v[164:167], v[56:59]
	v_mfma_f32_16x16x32_bf16 v[44:47], v[132:135], v[172:175], v[44:47]
	v_mfma_f32_16x16x32_bf16 v[40:43], v[140:143], v[172:175], v[40:43]
	v_mfma_f32_16x16x32_bf16 v[28:31], v[132:135], v[198:201], v[28:31]
	v_mfma_f32_16x16x32_bf16 v[24:27], v[140:143], v[198:201], v[24:27]
	v_mfma_f32_16x16x32_bf16 v[12:15], v[132:135], v[214:217], v[12:15]
	v_mfma_f32_16x16x32_bf16 v[8:11], v[140:143], v[214:217], v[8:11]
	v_mfma_f32_16x16x32_bf16 v[52:55], v[144:147], v[160:163], v[52:55]
	v_mfma_f32_16x16x32_bf16 v[48:51], v[152:155], v[160:163], v[48:51]
	v_mfma_f32_16x16x32_bf16 v[36:39], v[144:147], v[168:171], v[36:39]
	v_mfma_f32_16x16x32_bf16 v[32:35], v[152:155], v[168:171], v[32:35]
	v_mfma_f32_16x16x32_bf16 v[20:23], v[144:147], v[194:197], v[20:23]
	v_mfma_f32_16x16x32_bf16 v[16:19], v[152:155], v[194:197], v[16:19]
	v_mfma_f32_16x16x32_bf16 v[4:7], v[144:147], v[202:205], v[4:7]
	v_mfma_f32_16x16x32_bf16 v[0:3], v[152:155], v[202:205], v[0:3]
	v_mfma_f32_16x16x32_bf16 v[52:55], v[148:151], v[164:167], v[52:55]
	v_mfma_f32_16x16x32_bf16 v[48:51], v[156:159], v[164:167], v[48:51]
	v_mfma_f32_16x16x32_bf16 v[36:39], v[148:151], v[172:175], v[36:39]
	v_mfma_f32_16x16x32_bf16 v[32:35], v[156:159], v[172:175], v[32:35]
	v_mfma_f32_16x16x32_bf16 v[20:23], v[148:151], v[198:201], v[20:23]
	v_mfma_f32_16x16x32_bf16 v[16:19], v[156:159], v[198:201], v[16:19]
	v_mfma_f32_16x16x32_bf16 v[4:7], v[148:151], v[214:217], v[4:7]
	v_mfma_f32_16x16x32_bf16 v[0:3], v[156:159], v[214:217], v[0:3]
	s_barrier
	s_setprio 0
	s_add_i32 s66, 0, 0x18000
	s_add_i32 s67, 0, 0x1c000
	v_add_u32_e32 v140, s66, v208
	v_add_u32_e32 v156, s67, v208
	ds_read_b128 v[128:131], v140
	ds_read_b128 v[132:135], v140 offset:1024
	ds_read_b128 v[136:139], v140 offset:2048
	ds_read_b128 v[140:143], v140 offset:3072
	ds_read_b128 v[144:147], v156
	ds_read_b128 v[148:151], v156 offset:1024
	ds_read_b128 v[152:155], v156 offset:2048
	ds_read_b128 v[156:159], v156 offset:3072
	s_add_u32 s54, s54, s28
	s_addc_u32 s55, s55, s29
	s_mov_b32 m0, s27
	v_lshl_add_u64 v[230:231], s[54:55], 0, v[176:177]
	ds_read_b128 v[160:163], v212 offset:32768
	ds_read_b128 v[164:167], v212 offset:33792
	ds_read_b128 v[168:171], v212 offset:34816
	ds_read_b128 v[172:175], v212 offset:35840
	ds_read_b128 v[194:197], v212 offset:36864
	ds_read_b128 v[198:201], v212 offset:37888
	ds_read_b128 v[202:205], v212 offset:38912
	ds_read_b128 v[214:217], v212 offset:39936
	global_load_lds_dwordx4 v[230:231], off
	v_lshl_add_u64 v[230:231], s[54:55], 0, v[180:181]
	s_mov_b32 m0, s44
	s_nop 0
	global_load_lds_dwordx4 v[230:231], off
	s_waitcnt vmcnt(8)
	s_waitcnt lgkmcnt(0)
	s_setprio 1
	s_barrier
	s_waitcnt lgkmcnt(0)
	v_mfma_f32_16x16x32_bf16 v[120:123], v[128:131], v[160:163], v[120:123]
	v_mfma_f32_16x16x32_bf16 v[124:127], v[136:139], v[160:163], v[124:127]
	v_mfma_f32_16x16x32_bf16 v[108:111], v[128:131], v[168:171], v[108:111]
	v_mfma_f32_16x16x32_bf16 v[104:107], v[136:139], v[168:171], v[104:107]
	v_mfma_f32_16x16x32_bf16 v[92:95], v[128:131], v[194:197], v[92:95]
	v_mfma_f32_16x16x32_bf16 v[88:91], v[136:139], v[194:197], v[88:91]
	v_mfma_f32_16x16x32_bf16 v[76:79], v[128:131], v[202:205], v[76:79]
	v_mfma_f32_16x16x32_bf16 v[72:75], v[136:139], v[202:205], v[72:75]
	v_mfma_f32_16x16x32_bf16 v[120:123], v[132:135], v[164:167], v[120:123]
	v_mfma_f32_16x16x32_bf16 v[124:127], v[140:143], v[164:167], v[124:127]
	v_mfma_f32_16x16x32_bf16 v[108:111], v[132:135], v[172:175], v[108:111]
	v_mfma_f32_16x16x32_bf16 v[104:107], v[140:143], v[172:175], v[104:107]
	v_mfma_f32_16x16x32_bf16 v[92:95], v[132:135], v[198:201], v[92:95]
	v_mfma_f32_16x16x32_bf16 v[88:91], v[140:143], v[198:201], v[88:91]
	v_mfma_f32_16x16x32_bf16 v[76:79], v[132:135], v[214:217], v[76:79]
	v_mfma_f32_16x16x32_bf16 v[72:75], v[140:143], v[214:217], v[72:75]
	v_mfma_f32_16x16x32_bf16 v[116:119], v[144:147], v[160:163], v[116:119]
	v_mfma_f32_16x16x32_bf16 v[112:115], v[152:155], v[160:163], v[112:115]
	v_mfma_f32_16x16x32_bf16 v[100:103], v[144:147], v[168:171], v[100:103]
	v_mfma_f32_16x16x32_bf16 v[96:99], v[152:155], v[168:171], v[96:99]
	v_mfma_f32_16x16x32_bf16 v[84:87], v[144:147], v[194:197], v[84:87]
	v_mfma_f32_16x16x32_bf16 v[80:83], v[152:155], v[194:197], v[80:83]
	v_mfma_f32_16x16x32_bf16 v[68:71], v[144:147], v[202:205], v[68:71]
	v_mfma_f32_16x16x32_bf16 v[64:67], v[152:155], v[202:205], v[64:67]
	v_mfma_f32_16x16x32_bf16 v[116:119], v[148:151], v[164:167], v[116:119]
	v_mfma_f32_16x16x32_bf16 v[112:115], v[156:159], v[164:167], v[112:115]
	v_mfma_f32_16x16x32_bf16 v[100:103], v[148:151], v[172:175], v[100:103]
	v_mfma_f32_16x16x32_bf16 v[96:99], v[156:159], v[172:175], v[96:99]
	v_mfma_f32_16x16x32_bf16 v[84:87], v[148:151], v[198:201], v[84:87]
	v_mfma_f32_16x16x32_bf16 v[80:83], v[156:159], v[198:201], v[80:83]
	v_mfma_f32_16x16x32_bf16 v[68:71], v[148:151], v[214:217], v[68:71]
	v_mfma_f32_16x16x32_bf16 v[64:67], v[156:159], v[214:217], v[64:67]
	s_barrier
	s_setprio 0
	s_add_i32 s54, s66, s24
	v_lshl_add_u64 v[218:219], v[218:219], 0, s[42:43]
	s_mov_b32 m0, s54
	ds_read_b128 v[160:163], v212 offset:49152
	ds_read_b128 v[164:167], v212 offset:50176
	ds_read_b128 v[168:171], v212 offset:51200
	ds_read_b128 v[172:175], v212 offset:52224
	ds_read_b128 v[194:197], v212 offset:53248
	ds_read_b128 v[198:201], v212 offset:54272
	ds_read_b128 v[202:205], v212 offset:55296
	ds_read_b128 v[214:217], v212 offset:56320
	global_load_lds_dwordx4 v[218:219], off
	v_lshl_add_u64 v[218:219], v[220:221], 0, s[42:43]
	s_add_i32 m0, s54, 0x2000
	s_add_i32 s54, s67, s24
	global_load_lds_dwordx4 v[218:219], off
	v_lshl_add_u64 v[218:219], v[222:223], 0, s[42:43]
	s_mov_b32 m0, s54
	s_nop 0
	global_load_lds_dwordx4 v[218:219], off
	v_lshl_add_u64 v[218:219], v[224:225], 0, s[42:43]
	s_add_i32 m0, s54, 0x2000
	s_nop 0
	global_load_lds_dwordx4 v[218:219], off
	v_lshl_add_u64 v[218:219], v[226:227], 0, s[42:43]
	s_mov_b32 m0, s56
	s_nop 0
	global_load_lds_dwordx4 v[218:219], off
	v_lshl_add_u64 v[218:219], v[228:229], 0, s[42:43]
	s_mov_b32 m0, s57
	s_nop 0
	global_load_lds_dwordx4 v[218:219], off
	s_waitcnt vmcnt(8)
	s_waitcnt lgkmcnt(0)
	s_setprio 1
	s_barrier
	s_waitcnt lgkmcnt(0)
	v_mfma_f32_16x16x32_bf16 v[60:63], v[128:131], v[160:163], v[60:63]
	v_mfma_f32_16x16x32_bf16 v[56:59], v[136:139], v[160:163], v[56:59]
	v_mfma_f32_16x16x32_bf16 v[44:47], v[128:131], v[168:171], v[44:47]
	v_mfma_f32_16x16x32_bf16 v[40:43], v[136:139], v[168:171], v[40:43]
	v_mfma_f32_16x16x32_bf16 v[28:31], v[128:131], v[194:197], v[28:31]
	v_mfma_f32_16x16x32_bf16 v[24:27], v[136:139], v[194:197], v[24:27]
	v_mfma_f32_16x16x32_bf16 v[12:15], v[128:131], v[202:205], v[12:15]
	v_mfma_f32_16x16x32_bf16 v[8:11], v[136:139], v[202:205], v[8:11]
	v_mfma_f32_16x16x32_bf16 v[60:63], v[132:135], v[164:167], v[60:63]
	v_mfma_f32_16x16x32_bf16 v[56:59], v[140:143], v[164:167], v[56:59]
	v_mfma_f32_16x16x32_bf16 v[44:47], v[132:135], v[172:175], v[44:47]
	v_mfma_f32_16x16x32_bf16 v[40:43], v[140:143], v[172:175], v[40:43]
	v_mfma_f32_16x16x32_bf16 v[28:31], v[132:135], v[198:201], v[28:31]
	v_mfma_f32_16x16x32_bf16 v[24:27], v[140:143], v[198:201], v[24:27]
	v_mfma_f32_16x16x32_bf16 v[12:15], v[132:135], v[214:217], v[12:15]
	v_mfma_f32_16x16x32_bf16 v[8:11], v[140:143], v[214:217], v[8:11]
	v_mfma_f32_16x16x32_bf16 v[52:55], v[144:147], v[160:163], v[52:55]
	v_mfma_f32_16x16x32_bf16 v[48:51], v[152:155], v[160:163], v[48:51]
	v_mfma_f32_16x16x32_bf16 v[36:39], v[144:147], v[168:171], v[36:39]
	v_mfma_f32_16x16x32_bf16 v[32:35], v[152:155], v[168:171], v[32:35]
	v_mfma_f32_16x16x32_bf16 v[20:23], v[144:147], v[194:197], v[20:23]
	v_mfma_f32_16x16x32_bf16 v[16:19], v[152:155], v[194:197], v[16:19]
	v_mfma_f32_16x16x32_bf16 v[4:7], v[144:147], v[202:205], v[4:7]
	v_mfma_f32_16x16x32_bf16 v[0:3], v[152:155], v[202:205], v[0:3]
	v_mfma_f32_16x16x32_bf16 v[52:55], v[148:151], v[164:167], v[52:55]
	v_mfma_f32_16x16x32_bf16 v[48:51], v[156:159], v[164:167], v[48:51]
	v_mfma_f32_16x16x32_bf16 v[36:39], v[148:151], v[172:175], v[36:39]
	v_mfma_f32_16x16x32_bf16 v[32:35], v[156:159], v[172:175], v[32:35]
	v_mfma_f32_16x16x32_bf16 v[20:23], v[148:151], v[198:201], v[20:23]
	v_mfma_f32_16x16x32_bf16 v[16:19], v[156:159], v[198:201], v[16:19]
	v_mfma_f32_16x16x32_bf16 v[4:7], v[148:151], v[214:217], v[4:7]
	v_mfma_f32_16x16x32_bf16 v[0:3], v[156:159], v[214:217], v[0:3]
	s_barrier
	s_setprio 0
	s_add_u32 s52, s52, 0x100
	s_addc_u32 s53, s53, 0
	s_add_u32 s16, s16, 0x100
	s_addc_u32 s64, s64, 0
	s_cmp_ge_i32 s65, s58
	s_mov_b32 s54, s65
	s_cbranch_scc0 .LBB0_529

.LBB0_624:
	s_add_i32 vcc_lo, s90, 2
	s_add_u32 s44, s88, 0x80
	s_addc_u32 s45, s89, 0
	s_add_i32 vcc_hi, 0, 0x10000
	s_cmp_eq_u32 s55, s90
	s_cselect_b32 s91, s11, s45
	s_cselect_b32 s90, s10, s44
	v_add_u32_e32 v128, vcc_hi, v147
	s_cselect_b32 s45, s87, s16
	s_cselect_b32 s44, s86, s15
	s_add_i32 s58, 0, 0x14000
	ds_read_b128 v[156:159], v128
	ds_read_b128 v[160:163], v128 offset:1024
	ds_read_b128 v[164:167], v128 offset:2048
	ds_read_b128 v[168:171], v128 offset:3072
	v_add_u32_e32 v128, s58, v147
	ds_read_b128 v[172:175], v128
	ds_read_b128 v[184:187], v128 offset:1024
	ds_read_b128 v[188:191], v128 offset:2048
	ds_read_b128 v[192:195], v128 offset:3072
	v_lshl_add_u64 v[176:177], s[88:89], 0, v[138:139]
	s_add_i32 m0, s93, 0xc000
	ds_read_b128 v[204:207], v155
	ds_read_b128 v[208:211], v155 offset:1024
	ds_read_b128 v[212:215], v155 offset:2048
	ds_read_b128 v[216:219], v155 offset:3072
	ds_read_b128 v[220:223], v155 offset:4096
	ds_read_b128 v[224:227], v155 offset:5120
	ds_read_b128 v[228:231], v155 offset:6144
	ds_read_b128 v[232:235], v155 offset:7168
	global_load_lds_dwordx4 v[176:177], off
	v_lshl_add_u64 v[176:177], s[88:89], 0, v[140:141]
	s_add_i32 m0, s93, 0xe000
	s_nop 0
	global_load_lds_dwordx4 v[176:177], off
	s_waitcnt vmcnt(8)
	s_waitcnt lgkmcnt(0)
	s_setprio 1
	s_barrier
	s_waitcnt lgkmcnt(0)
	v_mfma_f32_16x16x32_bf16 v[124:127], v[156:159], v[204:207], v[124:127]
	v_mfma_f32_16x16x32_bf16 v[120:123], v[164:167], v[204:207], v[120:123]
	v_mfma_f32_16x16x32_bf16 v[108:111], v[156:159], v[212:215], v[108:111]
	v_mfma_f32_16x16x32_bf16 v[104:107], v[164:167], v[212:215], v[104:107]
	v_mfma_f32_16x16x32_bf16 v[92:95], v[156:159], v[220:223], v[92:95]
	v_mfma_f32_16x16x32_bf16 v[88:91], v[164:167], v[220:223], v[88:91]
	v_mfma_f32_16x16x32_bf16 v[76:79], v[156:159], v[228:231], v[76:79]
	v_mfma_f32_16x16x32_bf16 v[72:75], v[164:167], v[228:231], v[72:75]
	v_mfma_f32_16x16x32_bf16 v[124:127], v[160:163], v[208:211], v[124:127]
	v_mfma_f32_16x16x32_bf16 v[120:123], v[168:171], v[208:211], v[120:123]
	v_mfma_f32_16x16x32_bf16 v[108:111], v[160:163], v[216:219], v[108:111]
	v_mfma_f32_16x16x32_bf16 v[104:107], v[168:171], v[216:219], v[104:107]
	v_mfma_f32_16x16x32_bf16 v[92:95], v[160:163], v[224:227], v[92:95]
	v_mfma_f32_16x16x32_bf16 v[88:91], v[168:171], v[224:227], v[88:91]
	v_mfma_f32_16x16x32_bf16 v[76:79], v[160:163], v[232:235], v[76:79]
	v_mfma_f32_16x16x32_bf16 v[72:75], v[168:171], v[232:235], v[72:75]
	v_mfma_f32_16x16x32_bf16 v[116:119], v[172:175], v[204:207], v[116:119]
	v_mfma_f32_16x16x32_bf16 v[112:115], v[188:191], v[204:207], v[112:115]
	v_mfma_f32_16x16x32_bf16 v[100:103], v[172:175], v[212:215], v[100:103]
	v_mfma_f32_16x16x32_bf16 v[96:99], v[188:191], v[212:215], v[96:99]
	v_mfma_f32_16x16x32_bf16 v[84:87], v[172:175], v[220:223], v[84:87]
	v_mfma_f32_16x16x32_bf16 v[80:83], v[188:191], v[220:223], v[80:83]
	v_mfma_f32_16x16x32_bf16 v[68:71], v[172:175], v[228:231], v[68:71]
	v_mfma_f32_16x16x32_bf16 v[64:67], v[188:191], v[228:231], v[64:67]
	v_mfma_f32_16x16x32_bf16 v[116:119], v[184:187], v[208:211], v[116:119]
	v_mfma_f32_16x16x32_bf16 v[112:115], v[192:195], v[208:211], v[112:115]
	v_mfma_f32_16x16x32_bf16 v[100:103], v[184:187], v[216:219], v[100:103]
	v_mfma_f32_16x16x32_bf16 v[96:99], v[192:195], v[216:219], v[96:99]
	v_mfma_f32_16x16x32_bf16 v[84:87], v[184:187], v[224:227], v[84:87]
	v_mfma_f32_16x16x32_bf16 v[80:83], v[192:195], v[224:227], v[80:83]
	v_mfma_f32_16x16x32_bf16 v[68:71], v[184:187], v[232:235], v[68:71]
	v_mfma_f32_16x16x32_bf16 v[64:67], v[192:195], v[232:235], v[64:67]
	s_barrier
	s_setprio 0
	s_add_i32 vcc_hi, vcc_hi, s92
	v_lshl_add_u64 v[176:177], s[44:45], 0, v[134:135]
	s_mov_b32 m0, vcc_hi
	ds_read_b128 v[204:207], v155 offset:16384
	ds_read_b128 v[208:211], v155 offset:17408
	ds_read_b128 v[212:215], v155 offset:18432
	ds_read_b128 v[216:219], v155 offset:19456
	ds_read_b128 v[220:223], v155 offset:20480
	ds_read_b128 v[224:227], v155 offset:21504
	ds_read_b128 v[228:231], v155 offset:22528
	ds_read_b128 v[232:235], v155 offset:23552
	global_load_lds_dwordx4 v[176:177], off
	s_add_i32 m0, vcc_hi, 0x2000
	v_lshl_add_u64 v[178:179], s[44:45], 0, v[130:131]
	s_add_u32 s44, s44, s66
	s_addc_u32 s45, s45, s67
	s_add_i32 s58, s58, s92
	global_load_lds_dwordx4 v[178:179], off
	v_lshl_add_u64 v[180:181], s[44:45], 0, v[134:135]
	s_mov_b32 m0, s58
	v_lshl_add_u64 v[236:237], s[44:45], 0, v[130:131]
	global_load_lds_dwordx4 v[180:181], off
	s_add_i32 m0, s58, 0x2000
	v_lshl_add_u64 v[238:239], s[90:91], 0, v[136:137]
	global_load_lds_dwordx4 v[236:237], off
	s_mov_b32 m0, s93
	v_lshl_add_u64 v[240:241], s[90:91], 0, v[132:133]
	global_load_lds_dwordx4 v[238:239], off
	s_mov_b32 m0, s94
	s_nop 0
	global_load_lds_dwordx4 v[240:241], off
	s_waitcnt vmcnt(8)
	s_waitcnt lgkmcnt(0)
	s_setprio 1
	s_barrier
	s_waitcnt lgkmcnt(0)
	v_mfma_f32_16x16x32_bf16 v[60:63], v[156:159], v[204:207], v[60:63]
	v_mfma_f32_16x16x32_bf16 v[56:59], v[164:167], v[204:207], v[56:59]
	v_mfma_f32_16x16x32_bf16 v[44:47], v[156:159], v[212:215], v[44:47]
	v_mfma_f32_16x16x32_bf16 v[40:43], v[164:167], v[212:215], v[40:43]
	v_mfma_f32_16x16x32_bf16 v[28:31], v[156:159], v[220:223], v[28:31]
	v_mfma_f32_16x16x32_bf16 v[24:27], v[164:167], v[220:223], v[24:27]
	v_mfma_f32_16x16x32_bf16 v[12:15], v[156:159], v[228:231], v[12:15]
	v_mfma_f32_16x16x32_bf16 v[8:11], v[164:167], v[228:231], v[8:11]
	v_mfma_f32_16x16x32_bf16 v[60:63], v[160:163], v[208:211], v[60:63]
	v_mfma_f32_16x16x32_bf16 v[56:59], v[168:171], v[208:211], v[56:59]
	v_mfma_f32_16x16x32_bf16 v[44:47], v[160:163], v[216:219], v[44:47]
	v_mfma_f32_16x16x32_bf16 v[40:43], v[168:171], v[216:219], v[40:43]
	v_mfma_f32_16x16x32_bf16 v[28:31], v[160:163], v[224:227], v[28:31]
	v_mfma_f32_16x16x32_bf16 v[24:27], v[168:171], v[224:227], v[24:27]
	v_mfma_f32_16x16x32_bf16 v[12:15], v[160:163], v[232:235], v[12:15]
	v_mfma_f32_16x16x32_bf16 v[8:11], v[168:171], v[232:235], v[8:11]
	v_mfma_f32_16x16x32_bf16 v[52:55], v[172:175], v[204:207], v[52:55]
	v_mfma_f32_16x16x32_bf16 v[48:51], v[188:191], v[204:207], v[48:51]
	v_mfma_f32_16x16x32_bf16 v[36:39], v[172:175], v[212:215], v[36:39]
	v_mfma_f32_16x16x32_bf16 v[32:35], v[188:191], v[212:215], v[32:35]
	v_mfma_f32_16x16x32_bf16 v[20:23], v[172:175], v[220:223], v[20:23]
	v_mfma_f32_16x16x32_bf16 v[16:19], v[188:191], v[220:223], v[16:19]
	v_mfma_f32_16x16x32_bf16 v[4:7], v[172:175], v[228:231], v[4:7]
	v_mfma_f32_16x16x32_bf16 v[0:3], v[188:191], v[228:231], v[0:3]
	v_mfma_f32_16x16x32_bf16 v[52:55], v[184:187], v[208:211], v[52:55]
	v_mfma_f32_16x16x32_bf16 v[48:51], v[192:195], v[208:211], v[48:51]
	v_mfma_f32_16x16x32_bf16 v[36:39], v[184:187], v[216:219], v[36:39]
	v_mfma_f32_16x16x32_bf16 v[32:35], v[192:195], v[216:219], v[32:35]
	v_mfma_f32_16x16x32_bf16 v[20:23], v[184:187], v[224:227], v[20:23]
	v_mfma_f32_16x16x32_bf16 v[16:19], v[192:195], v[224:227], v[16:19]
	v_mfma_f32_16x16x32_bf16 v[4:7], v[184:187], v[232:235], v[4:7]
	v_mfma_f32_16x16x32_bf16 v[0:3], v[192:195], v[232:235], v[0:3]
	s_barrier
	s_setprio 0
	s_add_i32 s58, 0, 0x18000
	v_add_u32_e32 v128, s58, v147
	s_add_i32 vcc_hi, 0, 0x1c000
	ds_read_b128 v[156:159], v128
	ds_read_b128 v[160:163], v128 offset:1024
	ds_read_b128 v[164:167], v128 offset:2048
	ds_read_b128 v[168:171], v128 offset:3072
	v_add_u32_e32 v128, vcc_hi, v147
	ds_read_b128 v[172:175], v128
	ds_read_b128 v[184:187], v128 offset:1024
	ds_read_b128 v[188:191], v128 offset:2048
	ds_read_b128 v[192:195], v128 offset:3072
	s_add_u32 s44, s90, s66
	s_addc_u32 s45, s91, s67
	s_mov_b32 m0, s95
	v_lshl_add_u64 v[242:243], s[44:45], 0, v[136:137]
	ds_read_b128 v[204:207], v155 offset:32768
	ds_read_b128 v[208:211], v155 offset:33792
	ds_read_b128 v[212:215], v155 offset:34816
	ds_read_b128 v[216:219], v155 offset:35840
	ds_read_b128 v[220:223], v155 offset:36864
	ds_read_b128 v[224:227], v155 offset:37888
	ds_read_b128 v[228:231], v155 offset:38912
	ds_read_b128 v[232:235], v155 offset:39936
	global_load_lds_dwordx4 v[242:243], off
	v_lshl_add_u64 v[242:243], s[44:45], 0, v[132:133]
	s_mov_b32 m0, s96
	s_nop 0
	global_load_lds_dwordx4 v[242:243], off
	s_waitcnt vmcnt(8)
	s_waitcnt lgkmcnt(0)
	s_setprio 1
	s_barrier
	s_waitcnt lgkmcnt(0)
	v_mfma_f32_16x16x32_bf16 v[124:127], v[156:159], v[204:207], v[124:127]
	v_mfma_f32_16x16x32_bf16 v[120:123], v[164:167], v[204:207], v[120:123]
	v_mfma_f32_16x16x32_bf16 v[108:111], v[156:159], v[212:215], v[108:111]
	v_mfma_f32_16x16x32_bf16 v[104:107], v[164:167], v[212:215], v[104:107]
	v_mfma_f32_16x16x32_bf16 v[92:95], v[156:159], v[220:223], v[92:95]
	v_mfma_f32_16x16x32_bf16 v[88:91], v[164:167], v[220:223], v[88:91]
	v_mfma_f32_16x16x32_bf16 v[76:79], v[156:159], v[228:231], v[76:79]
	v_mfma_f32_16x16x32_bf16 v[72:75], v[164:167], v[228:231], v[72:75]
	v_mfma_f32_16x16x32_bf16 v[124:127], v[160:163], v[208:211], v[124:127]
	v_mfma_f32_16x16x32_bf16 v[120:123], v[168:171], v[208:211], v[120:123]
	v_mfma_f32_16x16x32_bf16 v[108:111], v[160:163], v[216:219], v[108:111]
	v_mfma_f32_16x16x32_bf16 v[104:107], v[168:171], v[216:219], v[104:107]
	v_mfma_f32_16x16x32_bf16 v[92:95], v[160:163], v[224:227], v[92:95]
	v_mfma_f32_16x16x32_bf16 v[88:91], v[168:171], v[224:227], v[88:91]
	v_mfma_f32_16x16x32_bf16 v[76:79], v[160:163], v[232:235], v[76:79]
	v_mfma_f32_16x16x32_bf16 v[72:75], v[168:171], v[232:235], v[72:75]
	v_mfma_f32_16x16x32_bf16 v[116:119], v[172:175], v[204:207], v[116:119]
	v_mfma_f32_16x16x32_bf16 v[112:115], v[188:191], v[204:207], v[112:115]
	v_mfma_f32_16x16x32_bf16 v[100:103], v[172:175], v[212:215], v[100:103]
	v_mfma_f32_16x16x32_bf16 v[96:99], v[188:191], v[212:215], v[96:99]
	v_mfma_f32_16x16x32_bf16 v[84:87], v[172:175], v[220:223], v[84:87]
	v_mfma_f32_16x16x32_bf16 v[80:83], v[188:191], v[220:223], v[80:83]
	v_mfma_f32_16x16x32_bf16 v[68:71], v[172:175], v[228:231], v[68:71]
	v_mfma_f32_16x16x32_bf16 v[64:67], v[188:191], v[228:231], v[64:67]
	v_mfma_f32_16x16x32_bf16 v[116:119], v[184:187], v[208:211], v[116:119]
	v_mfma_f32_16x16x32_bf16 v[112:115], v[192:195], v[208:211], v[112:115]
	v_mfma_f32_16x16x32_bf16 v[100:103], v[184:187], v[216:219], v[100:103]
	v_mfma_f32_16x16x32_bf16 v[96:99], v[192:195], v[216:219], v[96:99]
	v_mfma_f32_16x16x32_bf16 v[84:87], v[184:187], v[224:227], v[84:87]
	v_mfma_f32_16x16x32_bf16 v[80:83], v[192:195], v[224:227], v[80:83]
	v_mfma_f32_16x16x32_bf16 v[68:71], v[184:187], v[232:235], v[68:71]
	v_mfma_f32_16x16x32_bf16 v[64:67], v[192:195], v[232:235], v[64:67]
	s_barrier
	s_setprio 0
	s_add_i32 s44, s58, s92
	v_lshl_add_u64 v[176:177], v[176:177], 0, s[52:53]
	s_mov_b32 m0, s44
	ds_read_b128 v[204:207], v155 offset:49152
	ds_read_b128 v[208:211], v155 offset:50176
	ds_read_b128 v[212:215], v155 offset:51200
	ds_read_b128 v[216:219], v155 offset:52224
	ds_read_b128 v[220:223], v155 offset:53248
	ds_read_b128 v[224:227], v155 offset:54272
	ds_read_b128 v[228:231], v155 offset:55296
	ds_read_b128 v[232:235], v155 offset:56320
	global_load_lds_dwordx4 v[176:177], off
	v_lshl_add_u64 v[176:177], v[178:179], 0, s[52:53]
	s_add_i32 m0, s44, 0x2000
	s_add_i32 s44, vcc_hi, s92
	global_load_lds_dwordx4 v[176:177], off
	v_lshl_add_u64 v[176:177], v[180:181], 0, s[52:53]
	s_mov_b32 m0, s44
	s_nop 0
	global_load_lds_dwordx4 v[176:177], off
	v_lshl_add_u64 v[176:177], v[236:237], 0, s[52:53]
	s_add_i32 m0, s44, 0x2000
	s_nop 0
	global_load_lds_dwordx4 v[176:177], off
	v_lshl_add_u64 v[176:177], v[238:239], 0, s[52:53]
	s_mov_b32 m0, s97
	s_nop 0
	global_load_lds_dwordx4 v[176:177], off
	v_lshl_add_u64 v[176:177], v[240:241], 0, s[52:53]
	s_mov_b32 m0, s54
	s_nop 0
	global_load_lds_dwordx4 v[176:177], off
	s_waitcnt vmcnt(8)
	s_waitcnt lgkmcnt(0)
	s_setprio 1
	s_barrier
	s_waitcnt lgkmcnt(0)
	v_mfma_f32_16x16x32_bf16 v[60:63], v[156:159], v[204:207], v[60:63]
	v_mfma_f32_16x16x32_bf16 v[56:59], v[164:167], v[204:207], v[56:59]
	v_mfma_f32_16x16x32_bf16 v[44:47], v[156:159], v[212:215], v[44:47]
	v_mfma_f32_16x16x32_bf16 v[40:43], v[164:167], v[212:215], v[40:43]
	v_mfma_f32_16x16x32_bf16 v[28:31], v[156:159], v[220:223], v[28:31]
	v_mfma_f32_16x16x32_bf16 v[24:27], v[164:167], v[220:223], v[24:27]
	v_mfma_f32_16x16x32_bf16 v[12:15], v[156:159], v[228:231], v[12:15]
	v_mfma_f32_16x16x32_bf16 v[8:11], v[164:167], v[228:231], v[8:11]
	v_mfma_f32_16x16x32_bf16 v[60:63], v[160:163], v[208:211], v[60:63]
	v_mfma_f32_16x16x32_bf16 v[56:59], v[168:171], v[208:211], v[56:59]
	v_mfma_f32_16x16x32_bf16 v[44:47], v[160:163], v[216:219], v[44:47]
	v_mfma_f32_16x16x32_bf16 v[40:43], v[168:171], v[216:219], v[40:43]
	v_mfma_f32_16x16x32_bf16 v[28:31], v[160:163], v[224:227], v[28:31]
	v_mfma_f32_16x16x32_bf16 v[24:27], v[168:171], v[224:227], v[24:27]
	v_mfma_f32_16x16x32_bf16 v[12:15], v[160:163], v[232:235], v[12:15]
	v_mfma_f32_16x16x32_bf16 v[8:11], v[168:171], v[232:235], v[8:11]
	v_mfma_f32_16x16x32_bf16 v[52:55], v[172:175], v[204:207], v[52:55]
	v_mfma_f32_16x16x32_bf16 v[48:51], v[188:191], v[204:207], v[48:51]
	v_mfma_f32_16x16x32_bf16 v[36:39], v[172:175], v[212:215], v[36:39]
	v_mfma_f32_16x16x32_bf16 v[32:35], v[188:191], v[212:215], v[32:35]
	v_mfma_f32_16x16x32_bf16 v[20:23], v[172:175], v[220:223], v[20:23]
	v_mfma_f32_16x16x32_bf16 v[16:19], v[188:191], v[220:223], v[16:19]
	v_mfma_f32_16x16x32_bf16 v[4:7], v[172:175], v[228:231], v[4:7]
	v_mfma_f32_16x16x32_bf16 v[0:3], v[188:191], v[228:231], v[0:3]
	v_mfma_f32_16x16x32_bf16 v[52:55], v[184:187], v[208:211], v[52:55]
	v_mfma_f32_16x16x32_bf16 v[48:51], v[192:195], v[208:211], v[48:51]
	v_mfma_f32_16x16x32_bf16 v[36:39], v[184:187], v[216:219], v[36:39]
	v_mfma_f32_16x16x32_bf16 v[32:35], v[192:195], v[216:219], v[32:35]
	v_mfma_f32_16x16x32_bf16 v[20:23], v[184:187], v[224:227], v[20:23]
	v_mfma_f32_16x16x32_bf16 v[16:19], v[192:195], v[224:227], v[16:19]
	v_mfma_f32_16x16x32_bf16 v[4:7], v[184:187], v[232:235], v[4:7]
	v_mfma_f32_16x16x32_bf16 v[0:3], v[192:195], v[232:235], v[0:3]
	s_barrier
	s_setprio 0
	s_add_u32 s88, s88, 0x100
	s_addc_u32 s89, s89, 0
	s_add_u32 s15, s15, 0x100
	s_addc_u32 s16, s16, 0
	s_cmp_ge_i32 vcc_lo, s13
	s_mov_b32 s90, vcc_lo
	s_cbranch_scc0 .LBB0_624

.LBB0_725:
	s_add_i32 s82, s78, 2
	s_add_u32 s44, s76, 0x80
	s_addc_u32 s45, s77, 0
	s_add_i32 s58, 0, 0x10000
	s_cmp_eq_u32 s50, s78
	s_cselect_b32 s79, s9, s45
	s_cselect_b32 s78, s8, s44
	v_add_u32_e32 v140, s58, v143
	s_cselect_b32 s45, s75, s81
	s_cselect_b32 s44, s74, s80
	s_add_i32 s83, 0, 0x14000
	ds_read_b128 v[146:149], v140
	ds_read_b128 v[150:153], v140 offset:1024
	ds_read_b128 v[154:157], v140 offset:2048
	ds_read_b128 v[158:161], v140 offset:3072
	v_add_u32_e32 v140, s83, v143
	ds_read_b128 v[162:165], v140
	ds_read_b128 v[166:169], v140 offset:1024
	ds_read_b128 v[170:173], v140 offset:2048
	ds_read_b128 v[174:177], v140 offset:3072
	v_lshl_add_u64 v[140:141], s[76:77], 0, v[136:137]
	s_add_i32 m0, s23, 0xc000
	ds_read_b128 v[184:187], v145
	ds_read_b128 v[188:191], v145 offset:1024
	ds_read_b128 v[192:195], v145 offset:2048
	ds_read_b128 v[204:207], v145 offset:3072
	ds_read_b128 v[208:211], v145 offset:4096
	ds_read_b128 v[212:215], v145 offset:5120
	ds_read_b128 v[216:219], v145 offset:6144
	ds_read_b128 v[220:223], v145 offset:7168
	global_load_lds_dwordx4 v[140:141], off
	v_lshl_add_u64 v[140:141], s[76:77], 0, v[138:139]
	s_add_i32 m0, s23, 0xe000
	s_nop 0
	global_load_lds_dwordx4 v[140:141], off
	s_waitcnt vmcnt(8)
	s_waitcnt lgkmcnt(0)
	s_setprio 1
	s_barrier
	s_waitcnt lgkmcnt(0)
	v_mfma_f32_16x16x32_bf16 v[120:123], v[146:149], v[184:187], v[120:123]
	v_mfma_f32_16x16x32_bf16 v[124:127], v[154:157], v[184:187], v[124:127]
	v_mfma_f32_16x16x32_bf16 v[108:111], v[146:149], v[192:195], v[108:111]
	v_mfma_f32_16x16x32_bf16 v[104:107], v[154:157], v[192:195], v[104:107]
	v_mfma_f32_16x16x32_bf16 v[92:95], v[146:149], v[208:211], v[92:95]
	v_mfma_f32_16x16x32_bf16 v[88:91], v[154:157], v[208:211], v[88:91]
	v_mfma_f32_16x16x32_bf16 v[76:79], v[146:149], v[216:219], v[76:79]
	v_mfma_f32_16x16x32_bf16 v[72:75], v[154:157], v[216:219], v[72:75]
	v_mfma_f32_16x16x32_bf16 v[120:123], v[150:153], v[188:191], v[120:123]
	v_mfma_f32_16x16x32_bf16 v[124:127], v[158:161], v[188:191], v[124:127]
	v_mfma_f32_16x16x32_bf16 v[108:111], v[150:153], v[204:207], v[108:111]
	v_mfma_f32_16x16x32_bf16 v[104:107], v[158:161], v[204:207], v[104:107]
	v_mfma_f32_16x16x32_bf16 v[92:95], v[150:153], v[212:215], v[92:95]
	v_mfma_f32_16x16x32_bf16 v[88:91], v[158:161], v[212:215], v[88:91]
	v_mfma_f32_16x16x32_bf16 v[76:79], v[150:153], v[220:223], v[76:79]
	v_mfma_f32_16x16x32_bf16 v[72:75], v[158:161], v[220:223], v[72:75]
	v_mfma_f32_16x16x32_bf16 v[116:119], v[162:165], v[184:187], v[116:119]
	v_mfma_f32_16x16x32_bf16 v[112:115], v[170:173], v[184:187], v[112:115]
	v_mfma_f32_16x16x32_bf16 v[100:103], v[162:165], v[192:195], v[100:103]
	v_mfma_f32_16x16x32_bf16 v[96:99], v[170:173], v[192:195], v[96:99]
	v_mfma_f32_16x16x32_bf16 v[84:87], v[162:165], v[208:211], v[84:87]
	v_mfma_f32_16x16x32_bf16 v[80:83], v[170:173], v[208:211], v[80:83]
	v_mfma_f32_16x16x32_bf16 v[68:71], v[162:165], v[216:219], v[68:71]
	v_mfma_f32_16x16x32_bf16 v[64:67], v[170:173], v[216:219], v[64:67]
	v_mfma_f32_16x16x32_bf16 v[116:119], v[166:169], v[188:191], v[116:119]
	v_mfma_f32_16x16x32_bf16 v[112:115], v[174:177], v[188:191], v[112:115]
	v_mfma_f32_16x16x32_bf16 v[100:103], v[166:169], v[204:207], v[100:103]
	v_mfma_f32_16x16x32_bf16 v[96:99], v[174:177], v[204:207], v[96:99]
	v_mfma_f32_16x16x32_bf16 v[84:87], v[166:169], v[212:215], v[84:87]
	v_mfma_f32_16x16x32_bf16 v[80:83], v[174:177], v[212:215], v[80:83]
	v_mfma_f32_16x16x32_bf16 v[68:71], v[166:169], v[220:223], v[68:71]
	v_mfma_f32_16x16x32_bf16 v[64:67], v[174:177], v[220:223], v[64:67]
	s_barrier
	s_setprio 0
	s_add_i32 s58, s58, s22
	v_lshl_add_u64 v[140:141], s[44:45], 0, v[128:129]
	s_mov_b32 m0, s58
	ds_read_b128 v[184:187], v145 offset:16384
	ds_read_b128 v[188:191], v145 offset:17408
	ds_read_b128 v[192:195], v145 offset:18432
	ds_read_b128 v[204:207], v145 offset:19456
	ds_read_b128 v[208:211], v145 offset:20480
	ds_read_b128 v[212:215], v145 offset:21504
	ds_read_b128 v[216:219], v145 offset:22528
	ds_read_b128 v[220:223], v145 offset:23552
	global_load_lds_dwordx4 v[140:141], off
	s_add_i32 m0, s58, 0x2000
	v_lshl_add_u64 v[178:179], s[44:45], 0, v[130:131]
	s_add_u32 s44, s44, s10
	s_addc_u32 s45, s45, s11
	s_add_i32 s58, s83, s22
	global_load_lds_dwordx4 v[178:179], off
	v_lshl_add_u64 v[180:181], s[44:45], 0, v[128:129]
	s_mov_b32 m0, s58
	v_lshl_add_u64 v[224:225], s[44:45], 0, v[130:131]
	global_load_lds_dwordx4 v[180:181], off
	s_add_i32 m0, s58, 0x2000
	v_lshl_add_u64 v[226:227], s[78:79], 0, v[134:135]
	global_load_lds_dwordx4 v[224:225], off
	s_mov_b32 m0, s23
	v_lshl_add_u64 v[228:229], s[78:79], 0, v[132:133]
	global_load_lds_dwordx4 v[226:227], off
	s_mov_b32 m0, s29
	s_nop 0
	global_load_lds_dwordx4 v[228:229], off
	s_waitcnt vmcnt(8)
	s_waitcnt lgkmcnt(0)
	s_setprio 1
	s_barrier
	s_waitcnt lgkmcnt(0)
	v_mfma_f32_16x16x32_bf16 v[60:63], v[146:149], v[184:187], v[60:63]
	v_mfma_f32_16x16x32_bf16 v[56:59], v[154:157], v[184:187], v[56:59]
	v_mfma_f32_16x16x32_bf16 v[44:47], v[146:149], v[192:195], v[44:47]
	v_mfma_f32_16x16x32_bf16 v[40:43], v[154:157], v[192:195], v[40:43]
	v_mfma_f32_16x16x32_bf16 v[28:31], v[146:149], v[208:211], v[28:31]
	v_mfma_f32_16x16x32_bf16 v[24:27], v[154:157], v[208:211], v[24:27]
	v_mfma_f32_16x16x32_bf16 v[12:15], v[146:149], v[216:219], v[12:15]
	v_mfma_f32_16x16x32_bf16 v[8:11], v[154:157], v[216:219], v[8:11]
	v_mfma_f32_16x16x32_bf16 v[60:63], v[150:153], v[188:191], v[60:63]
	v_mfma_f32_16x16x32_bf16 v[56:59], v[158:161], v[188:191], v[56:59]
	v_mfma_f32_16x16x32_bf16 v[44:47], v[150:153], v[204:207], v[44:47]
	v_mfma_f32_16x16x32_bf16 v[40:43], v[158:161], v[204:207], v[40:43]
	v_mfma_f32_16x16x32_bf16 v[28:31], v[150:153], v[212:215], v[28:31]
	v_mfma_f32_16x16x32_bf16 v[24:27], v[158:161], v[212:215], v[24:27]
	v_mfma_f32_16x16x32_bf16 v[12:15], v[150:153], v[220:223], v[12:15]
	v_mfma_f32_16x16x32_bf16 v[8:11], v[158:161], v[220:223], v[8:11]
	v_mfma_f32_16x16x32_bf16 v[52:55], v[162:165], v[184:187], v[52:55]
	v_mfma_f32_16x16x32_bf16 v[48:51], v[170:173], v[184:187], v[48:51]
	v_mfma_f32_16x16x32_bf16 v[36:39], v[162:165], v[192:195], v[36:39]
	v_mfma_f32_16x16x32_bf16 v[32:35], v[170:173], v[192:195], v[32:35]
	v_mfma_f32_16x16x32_bf16 v[20:23], v[162:165], v[208:211], v[20:23]
	v_mfma_f32_16x16x32_bf16 v[16:19], v[170:173], v[208:211], v[16:19]
	v_mfma_f32_16x16x32_bf16 v[4:7], v[162:165], v[216:219], v[4:7]
	v_mfma_f32_16x16x32_bf16 v[0:3], v[170:173], v[216:219], v[0:3]
	v_mfma_f32_16x16x32_bf16 v[52:55], v[166:169], v[188:191], v[52:55]
	v_mfma_f32_16x16x32_bf16 v[48:51], v[174:177], v[188:191], v[48:51]
	v_mfma_f32_16x16x32_bf16 v[36:39], v[166:169], v[204:207], v[36:39]
	v_mfma_f32_16x16x32_bf16 v[32:35], v[174:177], v[204:207], v[32:35]
	v_mfma_f32_16x16x32_bf16 v[20:23], v[166:169], v[212:215], v[20:23]
	v_mfma_f32_16x16x32_bf16 v[16:19], v[174:177], v[212:215], v[16:19]
	v_mfma_f32_16x16x32_bf16 v[4:7], v[166:169], v[220:223], v[4:7]
	v_mfma_f32_16x16x32_bf16 v[0:3], v[174:177], v[220:223], v[0:3]
	s_barrier
	s_setprio 0
	s_add_i32 s58, 0, 0x18000
	s_add_i32 s83, 0, 0x1c000
	v_add_u32_e32 v158, s58, v143
	v_add_u32_e32 v174, s83, v143
	ds_read_b128 v[146:149], v158
	ds_read_b128 v[150:153], v158 offset:1024
	ds_read_b128 v[154:157], v158 offset:2048
	ds_read_b128 v[158:161], v158 offset:3072
	ds_read_b128 v[162:165], v174
	ds_read_b128 v[166:169], v174 offset:1024
	ds_read_b128 v[170:173], v174 offset:2048
	ds_read_b128 v[174:177], v174 offset:3072
	s_add_u32 s44, s78, s10
	s_addc_u32 s45, s79, s11
	s_mov_b32 m0, s39
	v_lshl_add_u64 v[230:231], s[44:45], 0, v[134:135]
	ds_read_b128 v[184:187], v145 offset:32768
	ds_read_b128 v[188:191], v145 offset:33792
	ds_read_b128 v[192:195], v145 offset:34816
	ds_read_b128 v[204:207], v145 offset:35840
	ds_read_b128 v[208:211], v145 offset:36864
	ds_read_b128 v[212:215], v145 offset:37888
	ds_read_b128 v[216:219], v145 offset:38912
	ds_read_b128 v[220:223], v145 offset:39936
	global_load_lds_dwordx4 v[230:231], off
	v_lshl_add_u64 v[230:231], s[44:45], 0, v[132:133]
	s_mov_b32 m0, s40
	s_nop 0
	global_load_lds_dwordx4 v[230:231], off
	s_waitcnt vmcnt(8)
	s_waitcnt lgkmcnt(0)
	s_setprio 1
	s_barrier
	s_waitcnt lgkmcnt(0)
	v_mfma_f32_16x16x32_bf16 v[120:123], v[146:149], v[184:187], v[120:123]
	v_mfma_f32_16x16x32_bf16 v[124:127], v[154:157], v[184:187], v[124:127]
	v_mfma_f32_16x16x32_bf16 v[108:111], v[146:149], v[192:195], v[108:111]
	v_mfma_f32_16x16x32_bf16 v[104:107], v[154:157], v[192:195], v[104:107]
	v_mfma_f32_16x16x32_bf16 v[92:95], v[146:149], v[208:211], v[92:95]
	v_mfma_f32_16x16x32_bf16 v[88:91], v[154:157], v[208:211], v[88:91]
	v_mfma_f32_16x16x32_bf16 v[76:79], v[146:149], v[216:219], v[76:79]
	v_mfma_f32_16x16x32_bf16 v[72:75], v[154:157], v[216:219], v[72:75]
	v_mfma_f32_16x16x32_bf16 v[120:123], v[150:153], v[188:191], v[120:123]
	v_mfma_f32_16x16x32_bf16 v[124:127], v[158:161], v[188:191], v[124:127]
	v_mfma_f32_16x16x32_bf16 v[108:111], v[150:153], v[204:207], v[108:111]
	v_mfma_f32_16x16x32_bf16 v[104:107], v[158:161], v[204:207], v[104:107]
	v_mfma_f32_16x16x32_bf16 v[92:95], v[150:153], v[212:215], v[92:95]
	v_mfma_f32_16x16x32_bf16 v[88:91], v[158:161], v[212:215], v[88:91]
	v_mfma_f32_16x16x32_bf16 v[76:79], v[150:153], v[220:223], v[76:79]
	v_mfma_f32_16x16x32_bf16 v[72:75], v[158:161], v[220:223], v[72:75]
	v_mfma_f32_16x16x32_bf16 v[116:119], v[162:165], v[184:187], v[116:119]
	v_mfma_f32_16x16x32_bf16 v[112:115], v[170:173], v[184:187], v[112:115]
	v_mfma_f32_16x16x32_bf16 v[100:103], v[162:165], v[192:195], v[100:103]
	v_mfma_f32_16x16x32_bf16 v[96:99], v[170:173], v[192:195], v[96:99]
	v_mfma_f32_16x16x32_bf16 v[84:87], v[162:165], v[208:211], v[84:87]
	v_mfma_f32_16x16x32_bf16 v[80:83], v[170:173], v[208:211], v[80:83]
	v_mfma_f32_16x16x32_bf16 v[68:71], v[162:165], v[216:219], v[68:71]
	v_mfma_f32_16x16x32_bf16 v[64:67], v[170:173], v[216:219], v[64:67]
	v_mfma_f32_16x16x32_bf16 v[116:119], v[166:169], v[188:191], v[116:119]
	v_mfma_f32_16x16x32_bf16 v[112:115], v[174:177], v[188:191], v[112:115]
	v_mfma_f32_16x16x32_bf16 v[100:103], v[166:169], v[204:207], v[100:103]
	v_mfma_f32_16x16x32_bf16 v[96:99], v[174:177], v[204:207], v[96:99]
	v_mfma_f32_16x16x32_bf16 v[84:87], v[166:169], v[212:215], v[84:87]
	v_mfma_f32_16x16x32_bf16 v[80:83], v[174:177], v[212:215], v[80:83]
	v_mfma_f32_16x16x32_bf16 v[68:71], v[166:169], v[220:223], v[68:71]
	v_mfma_f32_16x16x32_bf16 v[64:67], v[174:177], v[220:223], v[64:67]
	s_barrier
	s_setprio 0
	s_add_i32 s44, s58, s22
	v_lshl_add_u64 v[140:141], v[140:141], 0, s[52:53]
	s_mov_b32 m0, s44
	ds_read_b128 v[184:187], v145 offset:49152
	ds_read_b128 v[188:191], v145 offset:50176
	ds_read_b128 v[192:195], v145 offset:51200
	ds_read_b128 v[204:207], v145 offset:52224
	ds_read_b128 v[208:211], v145 offset:53248
	ds_read_b128 v[212:215], v145 offset:54272
	ds_read_b128 v[216:219], v145 offset:55296
	ds_read_b128 v[220:223], v145 offset:56320
	global_load_lds_dwordx4 v[140:141], off
	v_lshl_add_u64 v[140:141], v[178:179], 0, s[52:53]
	s_add_i32 m0, s44, 0x2000
	s_add_i32 s44, s83, s22
	global_load_lds_dwordx4 v[140:141], off
	v_lshl_add_u64 v[140:141], v[180:181], 0, s[52:53]
	s_mov_b32 m0, s44
	s_nop 0
	global_load_lds_dwordx4 v[140:141], off
	v_lshl_add_u64 v[140:141], v[224:225], 0, s[52:53]
	s_add_i32 m0, s44, 0x2000
	s_nop 0
	global_load_lds_dwordx4 v[140:141], off
	v_lshl_add_u64 v[140:141], v[226:227], 0, s[52:53]
	s_mov_b32 m0, s46
	s_nop 0
	global_load_lds_dwordx4 v[140:141], off
	v_lshl_add_u64 v[140:141], v[228:229], 0, s[52:53]
	s_mov_b32 m0, s47
	s_nop 0
	global_load_lds_dwordx4 v[140:141], off
	s_waitcnt vmcnt(8)
	s_waitcnt lgkmcnt(0)
	s_setprio 1
	s_barrier
	s_waitcnt lgkmcnt(0)
	v_mfma_f32_16x16x32_bf16 v[60:63], v[146:149], v[184:187], v[60:63]
	v_mfma_f32_16x16x32_bf16 v[56:59], v[154:157], v[184:187], v[56:59]
	v_mfma_f32_16x16x32_bf16 v[44:47], v[146:149], v[192:195], v[44:47]
	v_mfma_f32_16x16x32_bf16 v[40:43], v[154:157], v[192:195], v[40:43]
	v_mfma_f32_16x16x32_bf16 v[28:31], v[146:149], v[208:211], v[28:31]
	v_mfma_f32_16x16x32_bf16 v[24:27], v[154:157], v[208:211], v[24:27]
	v_mfma_f32_16x16x32_bf16 v[12:15], v[146:149], v[216:219], v[12:15]
	v_mfma_f32_16x16x32_bf16 v[8:11], v[154:157], v[216:219], v[8:11]
	v_mfma_f32_16x16x32_bf16 v[60:63], v[150:153], v[188:191], v[60:63]
	v_mfma_f32_16x16x32_bf16 v[56:59], v[158:161], v[188:191], v[56:59]
	v_mfma_f32_16x16x32_bf16 v[44:47], v[150:153], v[204:207], v[44:47]
	v_mfma_f32_16x16x32_bf16 v[40:43], v[158:161], v[204:207], v[40:43]
	v_mfma_f32_16x16x32_bf16 v[28:31], v[150:153], v[212:215], v[28:31]
	v_mfma_f32_16x16x32_bf16 v[24:27], v[158:161], v[212:215], v[24:27]
	v_mfma_f32_16x16x32_bf16 v[12:15], v[150:153], v[220:223], v[12:15]
	v_mfma_f32_16x16x32_bf16 v[8:11], v[158:161], v[220:223], v[8:11]
	v_mfma_f32_16x16x32_bf16 v[52:55], v[162:165], v[184:187], v[52:55]
	v_mfma_f32_16x16x32_bf16 v[48:51], v[170:173], v[184:187], v[48:51]
	v_mfma_f32_16x16x32_bf16 v[36:39], v[162:165], v[192:195], v[36:39]
	v_mfma_f32_16x16x32_bf16 v[32:35], v[170:173], v[192:195], v[32:35]
	v_mfma_f32_16x16x32_bf16 v[20:23], v[162:165], v[208:211], v[20:23]
	v_mfma_f32_16x16x32_bf16 v[16:19], v[170:173], v[208:211], v[16:19]
	v_mfma_f32_16x16x32_bf16 v[4:7], v[162:165], v[216:219], v[4:7]
	v_mfma_f32_16x16x32_bf16 v[0:3], v[170:173], v[216:219], v[0:3]
	v_mfma_f32_16x16x32_bf16 v[52:55], v[166:169], v[188:191], v[52:55]
	v_mfma_f32_16x16x32_bf16 v[48:51], v[174:177], v[188:191], v[48:51]
	v_mfma_f32_16x16x32_bf16 v[36:39], v[166:169], v[204:207], v[36:39]
	v_mfma_f32_16x16x32_bf16 v[32:35], v[174:177], v[204:207], v[32:35]
	v_mfma_f32_16x16x32_bf16 v[20:23], v[166:169], v[212:215], v[20:23]
	v_mfma_f32_16x16x32_bf16 v[16:19], v[174:177], v[212:215], v[16:19]
	v_mfma_f32_16x16x32_bf16 v[4:7], v[166:169], v[220:223], v[4:7]
	v_mfma_f32_16x16x32_bf16 v[0:3], v[174:177], v[220:223], v[0:3]
	s_barrier
	s_setprio 0
	s_add_u32 s76, s76, 0x100
	s_addc_u32 s77, s77, 0
	s_add_u32 s80, s80, 0x100
	s_addc_u32 s81, s81, 0
	s_cmp_ge_i32 s82, s41
	s_mov_b32 s78, s82
	s_cbranch_scc0 .LBB0_725

.LBB0_746:
	s_add_i32 s85, s82, 2
	s_add_u32 s44, s8, 0x80
	s_addc_u32 s45, s9, 0
	s_add_i32 s58, 0, 0x10000
	s_cmp_eq_u32 s50, s82
	s_cselect_b32 s83, s79, s45
	s_cselect_b32 s82, s78, s44
	v_add_u32_e32 v128, s58, v186
	s_cselect_b32 s45, s81, s84
	s_cselect_b32 s44, s80, s16
	s_add_i32 s88, 0, 0x14000
	ds_read_b128 v[130:133], v128
	ds_read_b128 v[134:137], v128 offset:1024
	ds_read_b128 v[138:141], v128 offset:2048
	ds_read_b128 v[142:145], v128 offset:3072
	v_add_u32_e32 v128, s88, v186
	ds_read_b128 v[146:149], v128
	ds_read_b128 v[150:153], v128 offset:1024
	ds_read_b128 v[154:157], v128 offset:2048
	ds_read_b128 v[158:161], v128 offset:3072
	v_lshl_add_u64 v[162:163], s[8:9], 0, v[172:173]
	s_add_i32 m0, s23, 0xc000
	ds_read_b128 v[204:207], v192
	ds_read_b128 v[208:211], v192 offset:1024
	ds_read_b128 v[212:215], v192 offset:2048
	ds_read_b128 v[216:219], v192 offset:3072
	ds_read_b128 v[220:223], v192 offset:4096
	ds_read_b128 v[224:227], v192 offset:5120
	ds_read_b128 v[228:231], v192 offset:6144
	ds_read_b128 v[232:235], v192 offset:7168
	global_load_lds_dwordx4 v[162:163], off
	v_lshl_add_u64 v[162:163], s[8:9], 0, v[174:175]
	s_add_i32 m0, s23, 0xe000
	s_nop 0
	global_load_lds_dwordx4 v[162:163], off
	s_waitcnt vmcnt(8)
	s_waitcnt lgkmcnt(0)
	s_setprio 1
	s_barrier
	s_waitcnt lgkmcnt(0)
	v_mfma_f32_16x16x32_bf16 v[124:127], v[130:133], v[204:207], v[124:127]
	v_mfma_f32_16x16x32_bf16 v[120:123], v[138:141], v[204:207], v[120:123]
	v_mfma_f32_16x16x32_bf16 v[108:111], v[130:133], v[212:215], v[108:111]
	v_mfma_f32_16x16x32_bf16 v[104:107], v[138:141], v[212:215], v[104:107]
	v_mfma_f32_16x16x32_bf16 v[92:95], v[130:133], v[220:223], v[92:95]
	v_mfma_f32_16x16x32_bf16 v[88:91], v[138:141], v[220:223], v[88:91]
	v_mfma_f32_16x16x32_bf16 v[76:79], v[130:133], v[228:231], v[76:79]
	v_mfma_f32_16x16x32_bf16 v[72:75], v[138:141], v[228:231], v[72:75]
	v_mfma_f32_16x16x32_bf16 v[124:127], v[134:137], v[208:211], v[124:127]
	v_mfma_f32_16x16x32_bf16 v[120:123], v[142:145], v[208:211], v[120:123]
	v_mfma_f32_16x16x32_bf16 v[108:111], v[134:137], v[216:219], v[108:111]
	v_mfma_f32_16x16x32_bf16 v[104:107], v[142:145], v[216:219], v[104:107]
	v_mfma_f32_16x16x32_bf16 v[92:95], v[134:137], v[224:227], v[92:95]
	v_mfma_f32_16x16x32_bf16 v[88:91], v[142:145], v[224:227], v[88:91]
	v_mfma_f32_16x16x32_bf16 v[76:79], v[134:137], v[232:235], v[76:79]
	v_mfma_f32_16x16x32_bf16 v[72:75], v[142:145], v[232:235], v[72:75]
	v_mfma_f32_16x16x32_bf16 v[116:119], v[146:149], v[204:207], v[116:119]
	v_mfma_f32_16x16x32_bf16 v[112:115], v[154:157], v[204:207], v[112:115]
	v_mfma_f32_16x16x32_bf16 v[100:103], v[146:149], v[212:215], v[100:103]
	v_mfma_f32_16x16x32_bf16 v[96:99], v[154:157], v[212:215], v[96:99]
	v_mfma_f32_16x16x32_bf16 v[84:87], v[146:149], v[220:223], v[84:87]
	v_mfma_f32_16x16x32_bf16 v[80:83], v[154:157], v[220:223], v[80:83]
	v_mfma_f32_16x16x32_bf16 v[68:71], v[146:149], v[228:231], v[68:71]
	v_mfma_f32_16x16x32_bf16 v[64:67], v[154:157], v[228:231], v[64:67]
	v_mfma_f32_16x16x32_bf16 v[116:119], v[150:153], v[208:211], v[116:119]
	v_mfma_f32_16x16x32_bf16 v[112:115], v[158:161], v[208:211], v[112:115]
	v_mfma_f32_16x16x32_bf16 v[100:103], v[150:153], v[216:219], v[100:103]
	v_mfma_f32_16x16x32_bf16 v[96:99], v[158:161], v[216:219], v[96:99]
	v_mfma_f32_16x16x32_bf16 v[84:87], v[150:153], v[224:227], v[84:87]
	v_mfma_f32_16x16x32_bf16 v[80:83], v[158:161], v[224:227], v[80:83]
	v_mfma_f32_16x16x32_bf16 v[68:71], v[150:153], v[232:235], v[68:71]
	v_mfma_f32_16x16x32_bf16 v[64:67], v[158:161], v[232:235], v[64:67]
	s_barrier
	s_setprio 0
	s_add_i32 s58, s58, s22
	v_lshl_add_u64 v[162:163], s[44:45], 0, v[168:169]
	s_mov_b32 m0, s58
	ds_read_b128 v[204:207], v192 offset:16384
	ds_read_b128 v[208:211], v192 offset:17408
	ds_read_b128 v[212:215], v192 offset:18432
	ds_read_b128 v[216:219], v192 offset:19456
	ds_read_b128 v[220:223], v192 offset:20480
	ds_read_b128 v[224:227], v192 offset:21504
	ds_read_b128 v[228:231], v192 offset:22528
	ds_read_b128 v[232:235], v192 offset:23552
	global_load_lds_dwordx4 v[162:163], off
	s_add_i32 m0, s58, 0x2000
	v_lshl_add_u64 v[176:177], s[44:45], 0, v[164:165]
	s_add_u32 s44, s44, s10
	s_addc_u32 s45, s45, s11
	s_add_i32 s58, s88, s22
	global_load_lds_dwordx4 v[176:177], off
	v_lshl_add_u64 v[178:179], s[44:45], 0, v[168:169]
	s_mov_b32 m0, s58
	v_lshl_add_u64 v[180:181], s[44:45], 0, v[164:165]
	global_load_lds_dwordx4 v[178:179], off
	s_add_i32 m0, s58, 0x2000
	v_lshl_add_u64 v[194:195], s[82:83], 0, v[170:171]
	global_load_lds_dwordx4 v[180:181], off
	s_mov_b32 m0, s23
	v_lshl_add_u64 v[236:237], s[82:83], 0, v[166:167]
	global_load_lds_dwordx4 v[194:195], off
	s_mov_b32 m0, s29
	s_nop 0
	global_load_lds_dwordx4 v[236:237], off
	s_waitcnt vmcnt(8)
	s_waitcnt lgkmcnt(0)
	s_setprio 1
	s_barrier
	s_waitcnt lgkmcnt(0)
	v_mfma_f32_16x16x32_bf16 v[60:63], v[130:133], v[204:207], v[60:63]
	v_mfma_f32_16x16x32_bf16 v[56:59], v[138:141], v[204:207], v[56:59]
	v_mfma_f32_16x16x32_bf16 v[44:47], v[130:133], v[212:215], v[44:47]
	v_mfma_f32_16x16x32_bf16 v[40:43], v[138:141], v[212:215], v[40:43]
	v_mfma_f32_16x16x32_bf16 v[28:31], v[130:133], v[220:223], v[28:31]
	v_mfma_f32_16x16x32_bf16 v[24:27], v[138:141], v[220:223], v[24:27]
	v_mfma_f32_16x16x32_bf16 v[12:15], v[130:133], v[228:231], v[12:15]
	v_mfma_f32_16x16x32_bf16 v[8:11], v[138:141], v[228:231], v[8:11]
	v_mfma_f32_16x16x32_bf16 v[60:63], v[134:137], v[208:211], v[60:63]
	v_mfma_f32_16x16x32_bf16 v[56:59], v[142:145], v[208:211], v[56:59]
	v_mfma_f32_16x16x32_bf16 v[44:47], v[134:137], v[216:219], v[44:47]
	v_mfma_f32_16x16x32_bf16 v[40:43], v[142:145], v[216:219], v[40:43]
	v_mfma_f32_16x16x32_bf16 v[28:31], v[134:137], v[224:227], v[28:31]
	v_mfma_f32_16x16x32_bf16 v[24:27], v[142:145], v[224:227], v[24:27]
	v_mfma_f32_16x16x32_bf16 v[12:15], v[134:137], v[232:235], v[12:15]
	v_mfma_f32_16x16x32_bf16 v[8:11], v[142:145], v[232:235], v[8:11]
	v_mfma_f32_16x16x32_bf16 v[52:55], v[146:149], v[204:207], v[52:55]
	v_mfma_f32_16x16x32_bf16 v[48:51], v[154:157], v[204:207], v[48:51]
	v_mfma_f32_16x16x32_bf16 v[36:39], v[146:149], v[212:215], v[36:39]
	v_mfma_f32_16x16x32_bf16 v[32:35], v[154:157], v[212:215], v[32:35]
	v_mfma_f32_16x16x32_bf16 v[20:23], v[146:149], v[220:223], v[20:23]
	v_mfma_f32_16x16x32_bf16 v[16:19], v[154:157], v[220:223], v[16:19]
	v_mfma_f32_16x16x32_bf16 v[4:7], v[146:149], v[228:231], v[4:7]
	v_mfma_f32_16x16x32_bf16 v[0:3], v[154:157], v[228:231], v[0:3]
	v_mfma_f32_16x16x32_bf16 v[52:55], v[150:153], v[208:211], v[52:55]
	v_mfma_f32_16x16x32_bf16 v[48:51], v[158:161], v[208:211], v[48:51]
	v_mfma_f32_16x16x32_bf16 v[36:39], v[150:153], v[216:219], v[36:39]
	v_mfma_f32_16x16x32_bf16 v[32:35], v[158:161], v[216:219], v[32:35]
	v_mfma_f32_16x16x32_bf16 v[20:23], v[150:153], v[224:227], v[20:23]
	v_mfma_f32_16x16x32_bf16 v[16:19], v[158:161], v[224:227], v[16:19]
	v_mfma_f32_16x16x32_bf16 v[4:7], v[150:153], v[232:235], v[4:7]
	v_mfma_f32_16x16x32_bf16 v[0:3], v[158:161], v[232:235], v[0:3]
	s_barrier
	s_setprio 0
	s_add_i32 s58, 0, 0x18000
	v_add_u32_e32 v128, s58, v186
	s_add_i32 s88, 0, 0x1c000
	ds_read_b128 v[130:133], v128
	ds_read_b128 v[134:137], v128 offset:1024
	ds_read_b128 v[138:141], v128 offset:2048
	ds_read_b128 v[142:145], v128 offset:3072
	v_add_u32_e32 v128, s88, v186
	ds_read_b128 v[146:149], v128
	ds_read_b128 v[150:153], v128 offset:1024
	ds_read_b128 v[154:157], v128 offset:2048
	ds_read_b128 v[158:161], v128 offset:3072
	s_add_u32 s44, s82, s10
	s_addc_u32 s45, s83, s11
	s_mov_b32 m0, s39
	v_lshl_add_u64 v[238:239], s[44:45], 0, v[170:171]
	ds_read_b128 v[204:207], v192 offset:32768
	ds_read_b128 v[208:211], v192 offset:33792
	ds_read_b128 v[212:215], v192 offset:34816
	ds_read_b128 v[216:219], v192 offset:35840
	ds_read_b128 v[220:223], v192 offset:36864
	ds_read_b128 v[224:227], v192 offset:37888
	ds_read_b128 v[228:231], v192 offset:38912
	ds_read_b128 v[232:235], v192 offset:39936
	global_load_lds_dwordx4 v[238:239], off
	v_lshl_add_u64 v[238:239], s[44:45], 0, v[166:167]
	s_mov_b32 m0, s40
	s_nop 0
	global_load_lds_dwordx4 v[238:239], off
	s_waitcnt vmcnt(8)
	s_waitcnt lgkmcnt(0)
	s_setprio 1
	s_barrier
	s_waitcnt lgkmcnt(0)
	v_mfma_f32_16x16x32_bf16 v[124:127], v[130:133], v[204:207], v[124:127]
	v_mfma_f32_16x16x32_bf16 v[120:123], v[138:141], v[204:207], v[120:123]
	v_mfma_f32_16x16x32_bf16 v[108:111], v[130:133], v[212:215], v[108:111]
	v_mfma_f32_16x16x32_bf16 v[104:107], v[138:141], v[212:215], v[104:107]
	v_mfma_f32_16x16x32_bf16 v[92:95], v[130:133], v[220:223], v[92:95]
	v_mfma_f32_16x16x32_bf16 v[88:91], v[138:141], v[220:223], v[88:91]
	v_mfma_f32_16x16x32_bf16 v[76:79], v[130:133], v[228:231], v[76:79]
	v_mfma_f32_16x16x32_bf16 v[72:75], v[138:141], v[228:231], v[72:75]
	v_mfma_f32_16x16x32_bf16 v[124:127], v[134:137], v[208:211], v[124:127]
	v_mfma_f32_16x16x32_bf16 v[120:123], v[142:145], v[208:211], v[120:123]
	v_mfma_f32_16x16x32_bf16 v[108:111], v[134:137], v[216:219], v[108:111]
	v_mfma_f32_16x16x32_bf16 v[104:107], v[142:145], v[216:219], v[104:107]
	v_mfma_f32_16x16x32_bf16 v[92:95], v[134:137], v[224:227], v[92:95]
	v_mfma_f32_16x16x32_bf16 v[88:91], v[142:145], v[224:227], v[88:91]
	v_mfma_f32_16x16x32_bf16 v[76:79], v[134:137], v[232:235], v[76:79]
	v_mfma_f32_16x16x32_bf16 v[72:75], v[142:145], v[232:235], v[72:75]
	v_mfma_f32_16x16x32_bf16 v[116:119], v[146:149], v[204:207], v[116:119]
	v_mfma_f32_16x16x32_bf16 v[112:115], v[154:157], v[204:207], v[112:115]
	v_mfma_f32_16x16x32_bf16 v[100:103], v[146:149], v[212:215], v[100:103]
	v_mfma_f32_16x16x32_bf16 v[96:99], v[154:157], v[212:215], v[96:99]
	v_mfma_f32_16x16x32_bf16 v[84:87], v[146:149], v[220:223], v[84:87]
	v_mfma_f32_16x16x32_bf16 v[80:83], v[154:157], v[220:223], v[80:83]
	v_mfma_f32_16x16x32_bf16 v[68:71], v[146:149], v[228:231], v[68:71]
	v_mfma_f32_16x16x32_bf16 v[64:67], v[154:157], v[228:231], v[64:67]
	v_mfma_f32_16x16x32_bf16 v[116:119], v[150:153], v[208:211], v[116:119]
	v_mfma_f32_16x16x32_bf16 v[112:115], v[158:161], v[208:211], v[112:115]
	v_mfma_f32_16x16x32_bf16 v[100:103], v[150:153], v[216:219], v[100:103]
	v_mfma_f32_16x16x32_bf16 v[96:99], v[158:161], v[216:219], v[96:99]
	v_mfma_f32_16x16x32_bf16 v[84:87], v[150:153], v[224:227], v[84:87]
	v_mfma_f32_16x16x32_bf16 v[80:83], v[158:161], v[224:227], v[80:83]
	v_mfma_f32_16x16x32_bf16 v[68:71], v[150:153], v[232:235], v[68:71]
	v_mfma_f32_16x16x32_bf16 v[64:67], v[158:161], v[232:235], v[64:67]
	s_barrier
	s_setprio 0
	s_add_i32 s44, s58, s22
	v_lshl_add_u64 v[162:163], v[162:163], 0, s[52:53]
	s_mov_b32 m0, s44
	ds_read_b128 v[204:207], v192 offset:49152
	ds_read_b128 v[208:211], v192 offset:50176
	ds_read_b128 v[212:215], v192 offset:51200
	ds_read_b128 v[216:219], v192 offset:52224
	ds_read_b128 v[220:223], v192 offset:53248
	ds_read_b128 v[224:227], v192 offset:54272
	ds_read_b128 v[228:231], v192 offset:55296
	ds_read_b128 v[232:235], v192 offset:56320
	global_load_lds_dwordx4 v[162:163], off
	v_lshl_add_u64 v[162:163], v[176:177], 0, s[52:53]
	s_add_i32 m0, s44, 0x2000
	s_add_i32 s44, s88, s22
	global_load_lds_dwordx4 v[162:163], off
	v_lshl_add_u64 v[162:163], v[178:179], 0, s[52:53]
	s_mov_b32 m0, s44
	s_nop 0
	global_load_lds_dwordx4 v[162:163], off
	v_lshl_add_u64 v[162:163], v[180:181], 0, s[52:53]
	s_add_i32 m0, s44, 0x2000
	s_nop 0
	global_load_lds_dwordx4 v[162:163], off
	v_lshl_add_u64 v[162:163], v[194:195], 0, s[52:53]
	s_mov_b32 m0, s46
	s_nop 0
	global_load_lds_dwordx4 v[162:163], off
	v_lshl_add_u64 v[162:163], v[236:237], 0, s[52:53]
	s_mov_b32 m0, s47
	s_nop 0
	global_load_lds_dwordx4 v[162:163], off
	s_waitcnt vmcnt(8)
	s_waitcnt lgkmcnt(0)
	s_setprio 1
	s_barrier
	s_waitcnt lgkmcnt(0)
	v_mfma_f32_16x16x32_bf16 v[60:63], v[130:133], v[204:207], v[60:63]
	v_mfma_f32_16x16x32_bf16 v[56:59], v[138:141], v[204:207], v[56:59]
	v_mfma_f32_16x16x32_bf16 v[44:47], v[130:133], v[212:215], v[44:47]
	v_mfma_f32_16x16x32_bf16 v[40:43], v[138:141], v[212:215], v[40:43]
	v_mfma_f32_16x16x32_bf16 v[28:31], v[130:133], v[220:223], v[28:31]
	v_mfma_f32_16x16x32_bf16 v[24:27], v[138:141], v[220:223], v[24:27]
	v_mfma_f32_16x16x32_bf16 v[12:15], v[130:133], v[228:231], v[12:15]
	v_mfma_f32_16x16x32_bf16 v[8:11], v[138:141], v[228:231], v[8:11]
	v_mfma_f32_16x16x32_bf16 v[60:63], v[134:137], v[208:211], v[60:63]
	v_mfma_f32_16x16x32_bf16 v[56:59], v[142:145], v[208:211], v[56:59]
	v_mfma_f32_16x16x32_bf16 v[44:47], v[134:137], v[216:219], v[44:47]
	v_mfma_f32_16x16x32_bf16 v[40:43], v[142:145], v[216:219], v[40:43]
	v_mfma_f32_16x16x32_bf16 v[28:31], v[134:137], v[224:227], v[28:31]
	v_mfma_f32_16x16x32_bf16 v[24:27], v[142:145], v[224:227], v[24:27]
	v_mfma_f32_16x16x32_bf16 v[12:15], v[134:137], v[232:235], v[12:15]
	v_mfma_f32_16x16x32_bf16 v[8:11], v[142:145], v[232:235], v[8:11]
	v_mfma_f32_16x16x32_bf16 v[52:55], v[146:149], v[204:207], v[52:55]
	v_mfma_f32_16x16x32_bf16 v[48:51], v[154:157], v[204:207], v[48:51]
	v_mfma_f32_16x16x32_bf16 v[36:39], v[146:149], v[212:215], v[36:39]
	v_mfma_f32_16x16x32_bf16 v[32:35], v[154:157], v[212:215], v[32:35]
	v_mfma_f32_16x16x32_bf16 v[20:23], v[146:149], v[220:223], v[20:23]
	v_mfma_f32_16x16x32_bf16 v[16:19], v[154:157], v[220:223], v[16:19]
	v_mfma_f32_16x16x32_bf16 v[4:7], v[146:149], v[228:231], v[4:7]
	v_mfma_f32_16x16x32_bf16 v[0:3], v[154:157], v[228:231], v[0:3]
	v_mfma_f32_16x16x32_bf16 v[52:55], v[150:153], v[208:211], v[52:55]
	v_mfma_f32_16x16x32_bf16 v[48:51], v[158:161], v[208:211], v[48:51]
	v_mfma_f32_16x16x32_bf16 v[36:39], v[150:153], v[216:219], v[36:39]
	v_mfma_f32_16x16x32_bf16 v[32:35], v[158:161], v[216:219], v[32:35]
	v_mfma_f32_16x16x32_bf16 v[20:23], v[150:153], v[224:227], v[20:23]
	v_mfma_f32_16x16x32_bf16 v[16:19], v[158:161], v[224:227], v[16:19]
	v_mfma_f32_16x16x32_bf16 v[4:7], v[150:153], v[232:235], v[4:7]
	v_mfma_f32_16x16x32_bf16 v[0:3], v[158:161], v[232:235], v[0:3]
	s_barrier
	s_setprio 0
	s_add_u32 s8, s8, 0x100
	s_addc_u32 s9, s9, 0
	s_add_u32 s16, s16, 0x100
	s_addc_u32 s84, s84, 0
	s_cmp_ge_i32 s85, s41
	s_mov_b32 s82, s85
	s_cbranch_scc0 .LBB0_746

.LBB0_950:
	s_add_i32 s87, s55, 2
	s_add_u32 s44, s80, 0x80
	s_addc_u32 s45, s81, 0
	s_add_i32 s58, 0, 0x10000
	s_cmp_eq_u32 s29, s55
	s_cselect_b32 s83, s11, s45
	s_cselect_b32 s82, s10, s44
	v_add_u32_e32 v128, s58, v185
	s_cselect_b32 s45, s79, s54
	s_cselect_b32 s44, s78, s16
	s_add_i32 s55, 0, 0x14000
	ds_read_b128 v[130:133], v128
	ds_read_b128 v[134:137], v128 offset:1024
	ds_read_b128 v[138:141], v128 offset:2048
	ds_read_b128 v[142:145], v128 offset:3072
	v_add_u32_e32 v128, s55, v185
	ds_read_b128 v[146:149], v128
	ds_read_b128 v[150:153], v128 offset:1024
	ds_read_b128 v[166:169], v128 offset:2048
	ds_read_b128 v[170:173], v128 offset:3072
	v_lshl_add_u64 v[220:221], s[80:81], 0, v[162:163]
	s_add_i32 m0, s40, 0xc000
	ds_read_b128 v[174:177], v187
	ds_read_b128 v[178:181], v187 offset:1024
	ds_read_b128 v[188:191], v187 offset:2048
	ds_read_b128 v[192:195], v187 offset:3072
	ds_read_b128 v[204:207], v187 offset:4096
	ds_read_b128 v[208:211], v187 offset:5120
	ds_read_b128 v[212:215], v187 offset:6144
	ds_read_b128 v[216:219], v187 offset:7168
	global_load_lds_dwordx4 v[220:221], off
	v_lshl_add_u64 v[220:221], s[80:81], 0, v[164:165]
	s_add_i32 m0, s40, 0xe000
	s_nop 0
	global_load_lds_dwordx4 v[220:221], off
	s_waitcnt vmcnt(8)
	s_waitcnt lgkmcnt(0)
	s_setprio 1
	s_barrier
	s_waitcnt lgkmcnt(0)
	v_mfma_f32_16x16x32_bf16 v[124:127], v[130:133], v[174:177], v[124:127]
	v_mfma_f32_16x16x32_bf16 v[120:123], v[138:141], v[174:177], v[120:123]
	v_mfma_f32_16x16x32_bf16 v[108:111], v[130:133], v[188:191], v[108:111]
	v_mfma_f32_16x16x32_bf16 v[104:107], v[138:141], v[188:191], v[104:107]
	v_mfma_f32_16x16x32_bf16 v[92:95], v[130:133], v[204:207], v[92:95]
	v_mfma_f32_16x16x32_bf16 v[88:91], v[138:141], v[204:207], v[88:91]
	v_mfma_f32_16x16x32_bf16 v[76:79], v[130:133], v[212:215], v[76:79]
	v_mfma_f32_16x16x32_bf16 v[72:75], v[138:141], v[212:215], v[72:75]
	v_mfma_f32_16x16x32_bf16 v[124:127], v[134:137], v[178:181], v[124:127]
	v_mfma_f32_16x16x32_bf16 v[120:123], v[142:145], v[178:181], v[120:123]
	v_mfma_f32_16x16x32_bf16 v[108:111], v[134:137], v[192:195], v[108:111]
	v_mfma_f32_16x16x32_bf16 v[104:107], v[142:145], v[192:195], v[104:107]
	v_mfma_f32_16x16x32_bf16 v[92:95], v[134:137], v[208:211], v[92:95]
	v_mfma_f32_16x16x32_bf16 v[88:91], v[142:145], v[208:211], v[88:91]
	v_mfma_f32_16x16x32_bf16 v[76:79], v[134:137], v[216:219], v[76:79]
	v_mfma_f32_16x16x32_bf16 v[72:75], v[142:145], v[216:219], v[72:75]
	v_mfma_f32_16x16x32_bf16 v[116:119], v[146:149], v[174:177], v[116:119]
	v_mfma_f32_16x16x32_bf16 v[112:115], v[166:169], v[174:177], v[112:115]
	v_mfma_f32_16x16x32_bf16 v[100:103], v[146:149], v[188:191], v[100:103]
	v_mfma_f32_16x16x32_bf16 v[96:99], v[166:169], v[188:191], v[96:99]
	v_mfma_f32_16x16x32_bf16 v[84:87], v[146:149], v[204:207], v[84:87]
	v_mfma_f32_16x16x32_bf16 v[80:83], v[166:169], v[204:207], v[80:83]
	v_mfma_f32_16x16x32_bf16 v[68:71], v[146:149], v[212:215], v[68:71]
	v_mfma_f32_16x16x32_bf16 v[64:67], v[166:169], v[212:215], v[64:67]
	v_mfma_f32_16x16x32_bf16 v[116:119], v[150:153], v[178:181], v[116:119]
	v_mfma_f32_16x16x32_bf16 v[112:115], v[170:173], v[178:181], v[112:115]
	v_mfma_f32_16x16x32_bf16 v[100:103], v[150:153], v[192:195], v[100:103]
	v_mfma_f32_16x16x32_bf16 v[96:99], v[170:173], v[192:195], v[96:99]
	v_mfma_f32_16x16x32_bf16 v[84:87], v[150:153], v[208:211], v[84:87]
	v_mfma_f32_16x16x32_bf16 v[80:83], v[170:173], v[208:211], v[80:83]
	v_mfma_f32_16x16x32_bf16 v[68:71], v[150:153], v[216:219], v[68:71]
	v_mfma_f32_16x16x32_bf16 v[64:67], v[170:173], v[216:219], v[64:67]
	s_barrier
	s_setprio 0
	s_add_i32 s58, s58, s86
	v_lshl_add_u64 v[220:221], s[44:45], 0, v[158:159]
	s_mov_b32 m0, s58
	ds_read_b128 v[174:177], v187 offset:16384
	ds_read_b128 v[178:181], v187 offset:17408
	ds_read_b128 v[188:191], v187 offset:18432
	ds_read_b128 v[192:195], v187 offset:19456
	ds_read_b128 v[204:207], v187 offset:20480
	ds_read_b128 v[208:211], v187 offset:21504
	ds_read_b128 v[212:215], v187 offset:22528
	ds_read_b128 v[216:219], v187 offset:23552
	global_load_lds_dwordx4 v[220:221], off
	s_add_i32 m0, s58, 0x2000
	v_lshl_add_u64 v[222:223], s[44:45], 0, v[154:155]
	s_add_u32 s44, s44, s64
	s_addc_u32 s45, s45, s65
	s_add_i32 s55, s55, s86
	global_load_lds_dwordx4 v[222:223], off
	v_lshl_add_u64 v[224:225], s[44:45], 0, v[158:159]
	s_mov_b32 m0, s55
	v_lshl_add_u64 v[226:227], s[44:45], 0, v[154:155]
	global_load_lds_dwordx4 v[224:225], off
	s_add_i32 m0, s55, 0x2000
	v_lshl_add_u64 v[228:229], s[82:83], 0, v[160:161]
	global_load_lds_dwordx4 v[226:227], off
	s_mov_b32 m0, s40
	v_lshl_add_u64 v[230:231], s[82:83], 0, v[156:157]
	global_load_lds_dwordx4 v[228:229], off
	s_mov_b32 m0, s12
	s_nop 0
	global_load_lds_dwordx4 v[230:231], off
	s_waitcnt vmcnt(8)
	s_waitcnt lgkmcnt(0)
	s_setprio 1
	s_barrier
	s_waitcnt lgkmcnt(0)
	v_mfma_f32_16x16x32_bf16 v[60:63], v[130:133], v[174:177], v[60:63]
	v_mfma_f32_16x16x32_bf16 v[56:59], v[138:141], v[174:177], v[56:59]
	v_mfma_f32_16x16x32_bf16 v[44:47], v[130:133], v[188:191], v[44:47]
	v_mfma_f32_16x16x32_bf16 v[40:43], v[138:141], v[188:191], v[40:43]
	v_mfma_f32_16x16x32_bf16 v[28:31], v[130:133], v[204:207], v[28:31]
	v_mfma_f32_16x16x32_bf16 v[24:27], v[138:141], v[204:207], v[24:27]
	v_mfma_f32_16x16x32_bf16 v[12:15], v[130:133], v[212:215], v[12:15]
	v_mfma_f32_16x16x32_bf16 v[8:11], v[138:141], v[212:215], v[8:11]
	v_mfma_f32_16x16x32_bf16 v[60:63], v[134:137], v[178:181], v[60:63]
	v_mfma_f32_16x16x32_bf16 v[56:59], v[142:145], v[178:181], v[56:59]
	v_mfma_f32_16x16x32_bf16 v[44:47], v[134:137], v[192:195], v[44:47]
	v_mfma_f32_16x16x32_bf16 v[40:43], v[142:145], v[192:195], v[40:43]
	v_mfma_f32_16x16x32_bf16 v[28:31], v[134:137], v[208:211], v[28:31]
	v_mfma_f32_16x16x32_bf16 v[24:27], v[142:145], v[208:211], v[24:27]
	v_mfma_f32_16x16x32_bf16 v[12:15], v[134:137], v[216:219], v[12:15]
	v_mfma_f32_16x16x32_bf16 v[8:11], v[142:145], v[216:219], v[8:11]
	v_mfma_f32_16x16x32_bf16 v[52:55], v[146:149], v[174:177], v[52:55]
	v_mfma_f32_16x16x32_bf16 v[48:51], v[166:169], v[174:177], v[48:51]
	v_mfma_f32_16x16x32_bf16 v[36:39], v[146:149], v[188:191], v[36:39]
	v_mfma_f32_16x16x32_bf16 v[32:35], v[166:169], v[188:191], v[32:35]
	v_mfma_f32_16x16x32_bf16 v[20:23], v[146:149], v[204:207], v[20:23]
	v_mfma_f32_16x16x32_bf16 v[16:19], v[166:169], v[204:207], v[16:19]
	v_mfma_f32_16x16x32_bf16 v[4:7], v[146:149], v[212:215], v[4:7]
	v_mfma_f32_16x16x32_bf16 v[0:3], v[166:169], v[212:215], v[0:3]
	v_mfma_f32_16x16x32_bf16 v[52:55], v[150:153], v[178:181], v[52:55]
	v_mfma_f32_16x16x32_bf16 v[48:51], v[170:173], v[178:181], v[48:51]
	v_mfma_f32_16x16x32_bf16 v[36:39], v[150:153], v[192:195], v[36:39]
	v_mfma_f32_16x16x32_bf16 v[32:35], v[170:173], v[192:195], v[32:35]
	v_mfma_f32_16x16x32_bf16 v[20:23], v[150:153], v[208:211], v[20:23]
	v_mfma_f32_16x16x32_bf16 v[16:19], v[170:173], v[208:211], v[16:19]
	v_mfma_f32_16x16x32_bf16 v[4:7], v[150:153], v[216:219], v[4:7]
	v_mfma_f32_16x16x32_bf16 v[0:3], v[170:173], v[216:219], v[0:3]
	s_barrier
	s_setprio 0
	s_add_i32 s55, 0, 0x18000
	v_add_u32_e32 v128, s55, v185
	s_add_i32 s58, 0, 0x1c000
	ds_read_b128 v[130:133], v128
	ds_read_b128 v[134:137], v128 offset:1024
	ds_read_b128 v[138:141], v128 offset:2048
	ds_read_b128 v[142:145], v128 offset:3072
	v_add_u32_e32 v128, s58, v185
	ds_read_b128 v[146:149], v128
	ds_read_b128 v[150:153], v128 offset:1024
	ds_read_b128 v[166:169], v128 offset:2048
	ds_read_b128 v[170:173], v128 offset:3072
	s_add_u32 s44, s82, s64
	s_addc_u32 s45, s83, s65
	s_mov_b32 m0, s4
	v_lshl_add_u64 v[232:233], s[44:45], 0, v[160:161]
	ds_read_b128 v[174:177], v187 offset:32768
	ds_read_b128 v[178:181], v187 offset:33792
	ds_read_b128 v[188:191], v187 offset:34816
	ds_read_b128 v[192:195], v187 offset:35840
	ds_read_b128 v[204:207], v187 offset:36864
	ds_read_b128 v[208:211], v187 offset:37888
	ds_read_b128 v[212:215], v187 offset:38912
	ds_read_b128 v[216:219], v187 offset:39936
	global_load_lds_dwordx4 v[232:233], off
	v_lshl_add_u64 v[232:233], s[44:45], 0, v[156:157]
	s_mov_b32 m0, s5
	s_nop 0
	global_load_lds_dwordx4 v[232:233], off
	s_waitcnt vmcnt(8)
	s_waitcnt lgkmcnt(0)
	s_setprio 1
	s_barrier
	s_waitcnt lgkmcnt(0)
	v_mfma_f32_16x16x32_bf16 v[124:127], v[130:133], v[174:177], v[124:127]
	v_mfma_f32_16x16x32_bf16 v[120:123], v[138:141], v[174:177], v[120:123]
	v_mfma_f32_16x16x32_bf16 v[108:111], v[130:133], v[188:191], v[108:111]
	v_mfma_f32_16x16x32_bf16 v[104:107], v[138:141], v[188:191], v[104:107]
	v_mfma_f32_16x16x32_bf16 v[92:95], v[130:133], v[204:207], v[92:95]
	v_mfma_f32_16x16x32_bf16 v[88:91], v[138:141], v[204:207], v[88:91]
	v_mfma_f32_16x16x32_bf16 v[76:79], v[130:133], v[212:215], v[76:79]
	v_mfma_f32_16x16x32_bf16 v[72:75], v[138:141], v[212:215], v[72:75]
	v_mfma_f32_16x16x32_bf16 v[124:127], v[134:137], v[178:181], v[124:127]
	v_mfma_f32_16x16x32_bf16 v[120:123], v[142:145], v[178:181], v[120:123]
	v_mfma_f32_16x16x32_bf16 v[108:111], v[134:137], v[192:195], v[108:111]
	v_mfma_f32_16x16x32_bf16 v[104:107], v[142:145], v[192:195], v[104:107]
	v_mfma_f32_16x16x32_bf16 v[92:95], v[134:137], v[208:211], v[92:95]
	v_mfma_f32_16x16x32_bf16 v[88:91], v[142:145], v[208:211], v[88:91]
	v_mfma_f32_16x16x32_bf16 v[76:79], v[134:137], v[216:219], v[76:79]
	v_mfma_f32_16x16x32_bf16 v[72:75], v[142:145], v[216:219], v[72:75]
	v_mfma_f32_16x16x32_bf16 v[116:119], v[146:149], v[174:177], v[116:119]
	v_mfma_f32_16x16x32_bf16 v[112:115], v[166:169], v[174:177], v[112:115]
	v_mfma_f32_16x16x32_bf16 v[100:103], v[146:149], v[188:191], v[100:103]
	v_mfma_f32_16x16x32_bf16 v[96:99], v[166:169], v[188:191], v[96:99]
	v_mfma_f32_16x16x32_bf16 v[84:87], v[146:149], v[204:207], v[84:87]
	v_mfma_f32_16x16x32_bf16 v[80:83], v[166:169], v[204:207], v[80:83]
	v_mfma_f32_16x16x32_bf16 v[68:71], v[146:149], v[212:215], v[68:71]
	v_mfma_f32_16x16x32_bf16 v[64:67], v[166:169], v[212:215], v[64:67]
	v_mfma_f32_16x16x32_bf16 v[116:119], v[150:153], v[178:181], v[116:119]
	v_mfma_f32_16x16x32_bf16 v[112:115], v[170:173], v[178:181], v[112:115]
	v_mfma_f32_16x16x32_bf16 v[100:103], v[150:153], v[192:195], v[100:103]
	v_mfma_f32_16x16x32_bf16 v[96:99], v[170:173], v[192:195], v[96:99]
	v_mfma_f32_16x16x32_bf16 v[84:87], v[150:153], v[208:211], v[84:87]
	v_mfma_f32_16x16x32_bf16 v[80:83], v[170:173], v[208:211], v[80:83]
	v_mfma_f32_16x16x32_bf16 v[68:71], v[150:153], v[216:219], v[68:71]
	v_mfma_f32_16x16x32_bf16 v[64:67], v[170:173], v[216:219], v[64:67]
	s_barrier
	s_setprio 0
	s_add_i32 s44, s55, s86
	v_lshl_add_u64 v[220:221], v[220:221], 0, s[52:53]
	s_mov_b32 m0, s44
	ds_read_b128 v[174:177], v187 offset:49152
	ds_read_b128 v[178:181], v187 offset:50176
	ds_read_b128 v[188:191], v187 offset:51200
	ds_read_b128 v[192:195], v187 offset:52224
	ds_read_b128 v[204:207], v187 offset:53248
	ds_read_b128 v[208:211], v187 offset:54272
	ds_read_b128 v[212:215], v187 offset:55296
	ds_read_b128 v[216:219], v187 offset:56320
	global_load_lds_dwordx4 v[220:221], off
	v_lshl_add_u64 v[220:221], v[222:223], 0, s[52:53]
	s_add_i32 m0, s44, 0x2000
	s_add_i32 s44, s58, s86
	global_load_lds_dwordx4 v[220:221], off
	v_lshl_add_u64 v[220:221], v[224:225], 0, s[52:53]
	s_mov_b32 m0, s44
	s_nop 0
	global_load_lds_dwordx4 v[220:221], off
	v_lshl_add_u64 v[220:221], v[226:227], 0, s[52:53]
	s_add_i32 m0, s44, 0x2000
	s_nop 0
	global_load_lds_dwordx4 v[220:221], off
	v_lshl_add_u64 v[220:221], v[228:229], 0, s[52:53]
	s_mov_b32 m0, s22
	s_nop 0
	global_load_lds_dwordx4 v[220:221], off
	v_lshl_add_u64 v[220:221], v[230:231], 0, s[52:53]
	s_mov_b32 m0, s23
	s_nop 0
	global_load_lds_dwordx4 v[220:221], off
	s_waitcnt vmcnt(8)
	s_waitcnt lgkmcnt(0)
	s_setprio 1
	s_barrier
	s_waitcnt lgkmcnt(0)
	v_mfma_f32_16x16x32_bf16 v[60:63], v[130:133], v[174:177], v[60:63]
	v_mfma_f32_16x16x32_bf16 v[56:59], v[138:141], v[174:177], v[56:59]
	v_mfma_f32_16x16x32_bf16 v[44:47], v[130:133], v[188:191], v[44:47]
	v_mfma_f32_16x16x32_bf16 v[40:43], v[138:141], v[188:191], v[40:43]
	v_mfma_f32_16x16x32_bf16 v[28:31], v[130:133], v[204:207], v[28:31]
	v_mfma_f32_16x16x32_bf16 v[24:27], v[138:141], v[204:207], v[24:27]
	v_mfma_f32_16x16x32_bf16 v[12:15], v[130:133], v[212:215], v[12:15]
	v_mfma_f32_16x16x32_bf16 v[8:11], v[138:141], v[212:215], v[8:11]
	v_mfma_f32_16x16x32_bf16 v[60:63], v[134:137], v[178:181], v[60:63]
	v_mfma_f32_16x16x32_bf16 v[56:59], v[142:145], v[178:181], v[56:59]
	v_mfma_f32_16x16x32_bf16 v[44:47], v[134:137], v[192:195], v[44:47]
	v_mfma_f32_16x16x32_bf16 v[40:43], v[142:145], v[192:195], v[40:43]
	v_mfma_f32_16x16x32_bf16 v[28:31], v[134:137], v[208:211], v[28:31]
	v_mfma_f32_16x16x32_bf16 v[24:27], v[142:145], v[208:211], v[24:27]
	v_mfma_f32_16x16x32_bf16 v[12:15], v[134:137], v[216:219], v[12:15]
	v_mfma_f32_16x16x32_bf16 v[8:11], v[142:145], v[216:219], v[8:11]
	v_mfma_f32_16x16x32_bf16 v[52:55], v[146:149], v[174:177], v[52:55]
	v_mfma_f32_16x16x32_bf16 v[48:51], v[166:169], v[174:177], v[48:51]
	v_mfma_f32_16x16x32_bf16 v[36:39], v[146:149], v[188:191], v[36:39]
	v_mfma_f32_16x16x32_bf16 v[32:35], v[166:169], v[188:191], v[32:35]
	v_mfma_f32_16x16x32_bf16 v[20:23], v[146:149], v[204:207], v[20:23]
	v_mfma_f32_16x16x32_bf16 v[16:19], v[166:169], v[204:207], v[16:19]
	v_mfma_f32_16x16x32_bf16 v[4:7], v[146:149], v[212:215], v[4:7]
	v_mfma_f32_16x16x32_bf16 v[0:3], v[166:169], v[212:215], v[0:3]
	v_mfma_f32_16x16x32_bf16 v[52:55], v[150:153], v[178:181], v[52:55]
	v_mfma_f32_16x16x32_bf16 v[48:51], v[170:173], v[178:181], v[48:51]
	v_mfma_f32_16x16x32_bf16 v[36:39], v[150:153], v[192:195], v[36:39]
	v_mfma_f32_16x16x32_bf16 v[32:35], v[170:173], v[192:195], v[32:35]
	v_mfma_f32_16x16x32_bf16 v[20:23], v[150:153], v[208:211], v[20:23]
	v_mfma_f32_16x16x32_bf16 v[16:19], v[170:173], v[208:211], v[16:19]
	v_mfma_f32_16x16x32_bf16 v[4:7], v[150:153], v[216:219], v[4:7]
	v_mfma_f32_16x16x32_bf16 v[0:3], v[170:173], v[216:219], v[0:3]
	s_barrier
	s_setprio 0
	s_add_u32 s80, s80, 0x100
	s_addc_u32 s81, s81, 0
	s_add_u32 s16, s16, 0x100
	s_addc_u32 s54, s54, 0
	s_cmp_ge_i32 s87, s13
	s_mov_b32 s55, s87
	s_cbranch_scc0 .LBB0_950

.LBB0_1042:
	s_add_i32 s83, s78, 2
	s_add_u32 s44, s76, 0x80
	s_addc_u32 s45, s77, 0
	s_add_i32 s58, 0, 0x10000
	s_cmp_eq_u32 s54, s78
	s_cselect_b32 s79, s9, s45
	s_cselect_b32 s78, s8, s44
	s_cselect_b32 s45, s75, s82
	s_cselect_b32 s44, s74, s16
	s_add_i32 s84, 0, 0x14000
	v_add_u32_e32 v158, s58, v146
	v_add_u32_e32 v174, s84, v146
	ds_read_b128 v[142:145], v158
	ds_read_b128 v[150:153], v158 offset:1024
	ds_read_b128 v[154:157], v158 offset:2048
	ds_read_b128 v[158:161], v158 offset:3072
	ds_read_b128 v[162:165], v174
	ds_read_b128 v[166:169], v174 offset:1024
	ds_read_b128 v[170:173], v174 offset:2048
	ds_read_b128 v[174:177], v174 offset:3072
	v_lshl_add_u64 v[220:221], s[76:77], 0, v[138:139]
	s_add_i32 m0, s23, 0xc000
	ds_read_b128 v[178:181], v149
	ds_read_b128 v[184:187], v149 offset:1024
	ds_read_b128 v[188:191], v149 offset:2048
	ds_read_b128 v[192:195], v149 offset:3072
	ds_read_b128 v[204:207], v149 offset:4096
	ds_read_b128 v[208:211], v149 offset:5120
	ds_read_b128 v[212:215], v149 offset:6144
	ds_read_b128 v[216:219], v149 offset:7168
	global_load_lds_dwordx4 v[220:221], off
	v_lshl_add_u64 v[220:221], s[76:77], 0, v[140:141]
	s_add_i32 m0, s23, 0xe000
	s_nop 0
	global_load_lds_dwordx4 v[220:221], off
	s_waitcnt vmcnt(8)
	s_waitcnt lgkmcnt(0)
	s_setprio 1
	s_barrier
	s_waitcnt lgkmcnt(0)
	v_mfma_f32_16x16x32_bf16 v[120:123], v[142:145], v[178:181], v[120:123]
	v_mfma_f32_16x16x32_bf16 v[116:119], v[154:157], v[178:181], v[116:119]
	v_mfma_f32_16x16x32_bf16 v[108:111], v[142:145], v[188:191], v[108:111]
	v_mfma_f32_16x16x32_bf16 v[100:103], v[154:157], v[188:191], v[100:103]
	v_mfma_f32_16x16x32_bf16 v[92:95], v[142:145], v[204:207], v[92:95]
	v_mfma_f32_16x16x32_bf16 v[84:87], v[154:157], v[204:207], v[84:87]
	v_mfma_f32_16x16x32_bf16 v[76:79], v[142:145], v[212:215], v[76:79]
	v_mfma_f32_16x16x32_bf16 v[68:71], v[154:157], v[212:215], v[68:71]
	v_mfma_f32_16x16x32_bf16 v[120:123], v[150:153], v[184:187], v[120:123]
	v_mfma_f32_16x16x32_bf16 v[116:119], v[158:161], v[184:187], v[116:119]
	v_mfma_f32_16x16x32_bf16 v[108:111], v[150:153], v[192:195], v[108:111]
	v_mfma_f32_16x16x32_bf16 v[100:103], v[158:161], v[192:195], v[100:103]
	v_mfma_f32_16x16x32_bf16 v[92:95], v[150:153], v[208:211], v[92:95]
	v_mfma_f32_16x16x32_bf16 v[84:87], v[158:161], v[208:211], v[84:87]
	v_mfma_f32_16x16x32_bf16 v[76:79], v[150:153], v[216:219], v[76:79]
	v_mfma_f32_16x16x32_bf16 v[68:71], v[158:161], v[216:219], v[68:71]
	v_mfma_f32_16x16x32_bf16 v[124:127], v[162:165], v[178:181], v[124:127]
	v_mfma_f32_16x16x32_bf16 v[112:115], v[170:173], v[178:181], v[112:115]
	v_mfma_f32_16x16x32_bf16 v[104:107], v[162:165], v[188:191], v[104:107]
	v_mfma_f32_16x16x32_bf16 v[96:99], v[170:173], v[188:191], v[96:99]
	v_mfma_f32_16x16x32_bf16 v[88:91], v[162:165], v[204:207], v[88:91]
	v_mfma_f32_16x16x32_bf16 v[80:83], v[170:173], v[204:207], v[80:83]
	v_mfma_f32_16x16x32_bf16 v[72:75], v[162:165], v[212:215], v[72:75]
	v_mfma_f32_16x16x32_bf16 v[64:67], v[170:173], v[212:215], v[64:67]
	v_mfma_f32_16x16x32_bf16 v[124:127], v[166:169], v[184:187], v[124:127]
	v_mfma_f32_16x16x32_bf16 v[112:115], v[174:177], v[184:187], v[112:115]
	v_mfma_f32_16x16x32_bf16 v[104:107], v[166:169], v[192:195], v[104:107]
	v_mfma_f32_16x16x32_bf16 v[96:99], v[174:177], v[192:195], v[96:99]
	v_mfma_f32_16x16x32_bf16 v[88:91], v[166:169], v[208:211], v[88:91]
	v_mfma_f32_16x16x32_bf16 v[80:83], v[174:177], v[208:211], v[80:83]
	v_mfma_f32_16x16x32_bf16 v[72:75], v[166:169], v[216:219], v[72:75]
	v_mfma_f32_16x16x32_bf16 v[64:67], v[174:177], v[216:219], v[64:67]
	s_barrier
	s_setprio 0
	s_add_i32 s58, s58, s22
	v_lshl_add_u64 v[220:221], s[44:45], 0, v[128:129]
	s_mov_b32 m0, s58
	ds_read_b128 v[178:181], v149 offset:16384
	ds_read_b128 v[184:187], v149 offset:17408
	ds_read_b128 v[188:191], v149 offset:18432
	ds_read_b128 v[192:195], v149 offset:19456
	ds_read_b128 v[204:207], v149 offset:20480
	ds_read_b128 v[208:211], v149 offset:21504
	ds_read_b128 v[212:215], v149 offset:22528
	ds_read_b128 v[216:219], v149 offset:23552
	global_load_lds_dwordx4 v[220:221], off
	s_add_i32 m0, s58, 0x2000
	v_lshl_add_u64 v[222:223], s[44:45], 0, v[130:131]
	s_add_u32 s44, s44, s10
	s_addc_u32 s45, s45, s11
	s_add_i32 s58, s84, s22
	global_load_lds_dwordx4 v[222:223], off
	v_lshl_add_u64 v[224:225], s[44:45], 0, v[128:129]
	s_mov_b32 m0, s58
	v_lshl_add_u64 v[226:227], s[44:45], 0, v[130:131]
	global_load_lds_dwordx4 v[224:225], off
	s_add_i32 m0, s58, 0x2000
	v_lshl_add_u64 v[228:229], s[78:79], 0, v[134:135]
	global_load_lds_dwordx4 v[226:227], off
	s_mov_b32 m0, s23
	v_lshl_add_u64 v[230:231], s[78:79], 0, v[132:133]
	global_load_lds_dwordx4 v[228:229], off
	s_mov_b32 m0, s29
	s_nop 0
	global_load_lds_dwordx4 v[230:231], off
	s_waitcnt vmcnt(8)
	s_waitcnt lgkmcnt(0)
	s_setprio 1
	s_barrier
	s_waitcnt lgkmcnt(0)
	v_mfma_f32_16x16x32_bf16 v[60:63], v[142:145], v[178:181], v[60:63]
	v_mfma_f32_16x16x32_bf16 v[52:55], v[154:157], v[178:181], v[52:55]
	v_mfma_f32_16x16x32_bf16 v[44:47], v[142:145], v[188:191], v[44:47]
	v_mfma_f32_16x16x32_bf16 v[36:39], v[154:157], v[188:191], v[36:39]
	v_mfma_f32_16x16x32_bf16 v[28:31], v[142:145], v[204:207], v[28:31]
	v_mfma_f32_16x16x32_bf16 v[20:23], v[154:157], v[204:207], v[20:23]
	v_mfma_f32_16x16x32_bf16 v[12:15], v[142:145], v[212:215], v[12:15]
	v_mfma_f32_16x16x32_bf16 v[4:7], v[154:157], v[212:215], v[4:7]
	v_mfma_f32_16x16x32_bf16 v[60:63], v[150:153], v[184:187], v[60:63]
	v_mfma_f32_16x16x32_bf16 v[52:55], v[158:161], v[184:187], v[52:55]
	v_mfma_f32_16x16x32_bf16 v[44:47], v[150:153], v[192:195], v[44:47]
	v_mfma_f32_16x16x32_bf16 v[36:39], v[158:161], v[192:195], v[36:39]
	v_mfma_f32_16x16x32_bf16 v[28:31], v[150:153], v[208:211], v[28:31]
	v_mfma_f32_16x16x32_bf16 v[20:23], v[158:161], v[208:211], v[20:23]
	v_mfma_f32_16x16x32_bf16 v[12:15], v[150:153], v[216:219], v[12:15]
	v_mfma_f32_16x16x32_bf16 v[4:7], v[158:161], v[216:219], v[4:7]
	v_mfma_f32_16x16x32_bf16 v[56:59], v[162:165], v[178:181], v[56:59]
	v_mfma_f32_16x16x32_bf16 v[48:51], v[170:173], v[178:181], v[48:51]
	v_mfma_f32_16x16x32_bf16 v[40:43], v[162:165], v[188:191], v[40:43]
	v_mfma_f32_16x16x32_bf16 v[32:35], v[170:173], v[188:191], v[32:35]
	v_mfma_f32_16x16x32_bf16 v[24:27], v[162:165], v[204:207], v[24:27]
	v_mfma_f32_16x16x32_bf16 v[16:19], v[170:173], v[204:207], v[16:19]
	v_mfma_f32_16x16x32_bf16 v[8:11], v[162:165], v[212:215], v[8:11]
	v_mfma_f32_16x16x32_bf16 v[0:3], v[170:173], v[212:215], v[0:3]
	v_mfma_f32_16x16x32_bf16 v[56:59], v[166:169], v[184:187], v[56:59]
	v_mfma_f32_16x16x32_bf16 v[48:51], v[174:177], v[184:187], v[48:51]
	v_mfma_f32_16x16x32_bf16 v[40:43], v[166:169], v[192:195], v[40:43]
	v_mfma_f32_16x16x32_bf16 v[32:35], v[174:177], v[192:195], v[32:35]
	v_mfma_f32_16x16x32_bf16 v[24:27], v[166:169], v[208:211], v[24:27]
	v_mfma_f32_16x16x32_bf16 v[16:19], v[174:177], v[208:211], v[16:19]
	v_mfma_f32_16x16x32_bf16 v[8:11], v[166:169], v[216:219], v[8:11]
	v_mfma_f32_16x16x32_bf16 v[0:3], v[174:177], v[216:219], v[0:3]
	s_barrier
	s_setprio 0
	s_add_i32 s58, 0, 0x18000
	s_add_i32 s84, 0, 0x1c000
	v_add_u32_e32 v158, s58, v146
	v_add_u32_e32 v174, s84, v146
	ds_read_b128 v[142:145], v158
	ds_read_b128 v[150:153], v158 offset:1024
	ds_read_b128 v[154:157], v158 offset:2048
	ds_read_b128 v[158:161], v158 offset:3072
	ds_read_b128 v[162:165], v174
	ds_read_b128 v[166:169], v174 offset:1024
	ds_read_b128 v[170:173], v174 offset:2048
	ds_read_b128 v[174:177], v174 offset:3072
	s_add_u32 s44, s78, s10
	s_addc_u32 s45, s79, s11
	s_mov_b32 m0, s39
	v_lshl_add_u64 v[232:233], s[44:45], 0, v[134:135]
	ds_read_b128 v[178:181], v149 offset:32768
	ds_read_b128 v[184:187], v149 offset:33792
	ds_read_b128 v[188:191], v149 offset:34816
	ds_read_b128 v[192:195], v149 offset:35840
	ds_read_b128 v[204:207], v149 offset:36864
	ds_read_b128 v[208:211], v149 offset:37888
	ds_read_b128 v[212:215], v149 offset:38912
	ds_read_b128 v[216:219], v149 offset:39936
	global_load_lds_dwordx4 v[232:233], off
	v_lshl_add_u64 v[232:233], s[44:45], 0, v[132:133]
	s_mov_b32 m0, s40
	s_nop 0
	global_load_lds_dwordx4 v[232:233], off
	s_waitcnt vmcnt(8)
	s_waitcnt lgkmcnt(0)
	s_setprio 1
	s_barrier
	s_waitcnt lgkmcnt(0)
	v_mfma_f32_16x16x32_bf16 v[120:123], v[142:145], v[178:181], v[120:123]
	v_mfma_f32_16x16x32_bf16 v[116:119], v[154:157], v[178:181], v[116:119]
	v_mfma_f32_16x16x32_bf16 v[108:111], v[142:145], v[188:191], v[108:111]
	v_mfma_f32_16x16x32_bf16 v[100:103], v[154:157], v[188:191], v[100:103]
	v_mfma_f32_16x16x32_bf16 v[92:95], v[142:145], v[204:207], v[92:95]
	v_mfma_f32_16x16x32_bf16 v[84:87], v[154:157], v[204:207], v[84:87]
	v_mfma_f32_16x16x32_bf16 v[76:79], v[142:145], v[212:215], v[76:79]
	v_mfma_f32_16x16x32_bf16 v[68:71], v[154:157], v[212:215], v[68:71]
	v_mfma_f32_16x16x32_bf16 v[120:123], v[150:153], v[184:187], v[120:123]
	v_mfma_f32_16x16x32_bf16 v[116:119], v[158:161], v[184:187], v[116:119]
	v_mfma_f32_16x16x32_bf16 v[108:111], v[150:153], v[192:195], v[108:111]
	v_mfma_f32_16x16x32_bf16 v[100:103], v[158:161], v[192:195], v[100:103]
	v_mfma_f32_16x16x32_bf16 v[92:95], v[150:153], v[208:211], v[92:95]
	v_mfma_f32_16x16x32_bf16 v[84:87], v[158:161], v[208:211], v[84:87]
	v_mfma_f32_16x16x32_bf16 v[76:79], v[150:153], v[216:219], v[76:79]
	v_mfma_f32_16x16x32_bf16 v[68:71], v[158:161], v[216:219], v[68:71]
	v_mfma_f32_16x16x32_bf16 v[124:127], v[162:165], v[178:181], v[124:127]
	v_mfma_f32_16x16x32_bf16 v[112:115], v[170:173], v[178:181], v[112:115]
	v_mfma_f32_16x16x32_bf16 v[104:107], v[162:165], v[188:191], v[104:107]
	v_mfma_f32_16x16x32_bf16 v[96:99], v[170:173], v[188:191], v[96:99]
	v_mfma_f32_16x16x32_bf16 v[88:91], v[162:165], v[204:207], v[88:91]
	v_mfma_f32_16x16x32_bf16 v[80:83], v[170:173], v[204:207], v[80:83]
	v_mfma_f32_16x16x32_bf16 v[72:75], v[162:165], v[212:215], v[72:75]
	v_mfma_f32_16x16x32_bf16 v[64:67], v[170:173], v[212:215], v[64:67]
	v_mfma_f32_16x16x32_bf16 v[124:127], v[166:169], v[184:187], v[124:127]
	v_mfma_f32_16x16x32_bf16 v[112:115], v[174:177], v[184:187], v[112:115]
	v_mfma_f32_16x16x32_bf16 v[104:107], v[166:169], v[192:195], v[104:107]
	v_mfma_f32_16x16x32_bf16 v[96:99], v[174:177], v[192:195], v[96:99]
	v_mfma_f32_16x16x32_bf16 v[88:91], v[166:169], v[208:211], v[88:91]
	v_mfma_f32_16x16x32_bf16 v[80:83], v[174:177], v[208:211], v[80:83]
	v_mfma_f32_16x16x32_bf16 v[72:75], v[166:169], v[216:219], v[72:75]
	v_mfma_f32_16x16x32_bf16 v[64:67], v[174:177], v[216:219], v[64:67]
	s_barrier
	s_setprio 0
	s_add_i32 s44, s58, s22
	v_lshl_add_u64 v[220:221], v[220:221], 0, s[52:53]
	s_mov_b32 m0, s44
	ds_read_b128 v[178:181], v149 offset:49152
	ds_read_b128 v[184:187], v149 offset:50176
	ds_read_b128 v[188:191], v149 offset:51200
	ds_read_b128 v[192:195], v149 offset:52224
	ds_read_b128 v[204:207], v149 offset:53248
	ds_read_b128 v[208:211], v149 offset:54272
	ds_read_b128 v[212:215], v149 offset:55296
	ds_read_b128 v[216:219], v149 offset:56320
	global_load_lds_dwordx4 v[220:221], off
	v_lshl_add_u64 v[220:221], v[222:223], 0, s[52:53]
	s_add_i32 m0, s44, 0x2000
	s_add_i32 s44, s84, s22
	global_load_lds_dwordx4 v[220:221], off
	v_lshl_add_u64 v[220:221], v[224:225], 0, s[52:53]
	s_mov_b32 m0, s44
	s_nop 0
	global_load_lds_dwordx4 v[220:221], off
	v_lshl_add_u64 v[220:221], v[226:227], 0, s[52:53]
	s_add_i32 m0, s44, 0x2000
	s_nop 0
	global_load_lds_dwordx4 v[220:221], off
	v_lshl_add_u64 v[220:221], v[228:229], 0, s[52:53]
	s_mov_b32 m0, s41
	s_nop 0
	global_load_lds_dwordx4 v[220:221], off
	v_lshl_add_u64 v[220:221], v[230:231], 0, s[52:53]
	s_mov_b32 m0, s46
	s_nop 0
	global_load_lds_dwordx4 v[220:221], off
	s_waitcnt vmcnt(8)
	s_waitcnt lgkmcnt(0)
	s_setprio 1
	s_barrier
	s_waitcnt lgkmcnt(0)
	v_mfma_f32_16x16x32_bf16 v[60:63], v[142:145], v[178:181], v[60:63]
	v_mfma_f32_16x16x32_bf16 v[52:55], v[154:157], v[178:181], v[52:55]
	v_mfma_f32_16x16x32_bf16 v[44:47], v[142:145], v[188:191], v[44:47]
	v_mfma_f32_16x16x32_bf16 v[36:39], v[154:157], v[188:191], v[36:39]
	v_mfma_f32_16x16x32_bf16 v[28:31], v[142:145], v[204:207], v[28:31]
	v_mfma_f32_16x16x32_bf16 v[20:23], v[154:157], v[204:207], v[20:23]
	v_mfma_f32_16x16x32_bf16 v[12:15], v[142:145], v[212:215], v[12:15]
	v_mfma_f32_16x16x32_bf16 v[4:7], v[154:157], v[212:215], v[4:7]
	v_mfma_f32_16x16x32_bf16 v[60:63], v[150:153], v[184:187], v[60:63]
	v_mfma_f32_16x16x32_bf16 v[52:55], v[158:161], v[184:187], v[52:55]
	v_mfma_f32_16x16x32_bf16 v[44:47], v[150:153], v[192:195], v[44:47]
	v_mfma_f32_16x16x32_bf16 v[36:39], v[158:161], v[192:195], v[36:39]
	v_mfma_f32_16x16x32_bf16 v[28:31], v[150:153], v[208:211], v[28:31]
	v_mfma_f32_16x16x32_bf16 v[20:23], v[158:161], v[208:211], v[20:23]
	v_mfma_f32_16x16x32_bf16 v[12:15], v[150:153], v[216:219], v[12:15]
	v_mfma_f32_16x16x32_bf16 v[4:7], v[158:161], v[216:219], v[4:7]
	v_mfma_f32_16x16x32_bf16 v[56:59], v[162:165], v[178:181], v[56:59]
	v_mfma_f32_16x16x32_bf16 v[48:51], v[170:173], v[178:181], v[48:51]
	v_mfma_f32_16x16x32_bf16 v[40:43], v[162:165], v[188:191], v[40:43]
	v_mfma_f32_16x16x32_bf16 v[32:35], v[170:173], v[188:191], v[32:35]
	v_mfma_f32_16x16x32_bf16 v[24:27], v[162:165], v[204:207], v[24:27]
	v_mfma_f32_16x16x32_bf16 v[16:19], v[170:173], v[204:207], v[16:19]
	v_mfma_f32_16x16x32_bf16 v[8:11], v[162:165], v[212:215], v[8:11]
	v_mfma_f32_16x16x32_bf16 v[0:3], v[170:173], v[212:215], v[0:3]
	v_mfma_f32_16x16x32_bf16 v[56:59], v[166:169], v[184:187], v[56:59]
	v_mfma_f32_16x16x32_bf16 v[48:51], v[174:177], v[184:187], v[48:51]
	v_mfma_f32_16x16x32_bf16 v[40:43], v[166:169], v[192:195], v[40:43]
	v_mfma_f32_16x16x32_bf16 v[32:35], v[174:177], v[192:195], v[32:35]
	v_mfma_f32_16x16x32_bf16 v[24:27], v[166:169], v[208:211], v[24:27]
	v_mfma_f32_16x16x32_bf16 v[16:19], v[174:177], v[208:211], v[16:19]
	v_mfma_f32_16x16x32_bf16 v[8:11], v[166:169], v[216:219], v[8:11]
	v_mfma_f32_16x16x32_bf16 v[0:3], v[174:177], v[216:219], v[0:3]
	s_barrier
	s_setprio 0
	s_add_u32 s76, s76, 0x100
	s_addc_u32 s77, s77, 0
	s_add_u32 s16, s16, 0x100
	s_addc_u32 s82, s82, 0
	s_cmp_ge_i32 s83, s47
	s_mov_b32 s78, s83
	s_cbranch_scc0 .LBB0_1042

.LBB0_1122:
	s_add_i32 s65, s55, 2
	s_add_u32 s44, s86, 0x80
	s_addc_u32 s45, s87, 0
	s_add_i32 s58, 0, 0x10000
	s_cmp_eq_u32 s29, s55
	s_cselect_b32 s89, s11, s45
	s_cselect_b32 s88, s10, s44
	v_add_u32_e32 v128, s58, v185
	s_cselect_b32 s45, s85, s54
	s_cselect_b32 s44, s84, s16
	s_add_i32 s55, 0, 0x14000
	ds_read_b128 v[130:133], v128
	ds_read_b128 v[134:137], v128 offset:1024
	ds_read_b128 v[138:141], v128 offset:2048
	ds_read_b128 v[142:145], v128 offset:3072
	v_add_u32_e32 v128, s55, v185
	ds_read_b128 v[146:149], v128
	ds_read_b128 v[150:153], v128 offset:1024
	ds_read_b128 v[166:169], v128 offset:2048
	ds_read_b128 v[170:173], v128 offset:3072
	v_lshl_add_u64 v[220:221], s[86:87], 0, v[162:163]
	s_add_i32 m0, s40, 0xc000
	ds_read_b128 v[174:177], v187
	ds_read_b128 v[178:181], v187 offset:1024
	ds_read_b128 v[188:191], v187 offset:2048
	ds_read_b128 v[192:195], v187 offset:3072
	ds_read_b128 v[204:207], v187 offset:4096
	ds_read_b128 v[208:211], v187 offset:5120
	ds_read_b128 v[212:215], v187 offset:6144
	ds_read_b128 v[216:219], v187 offset:7168
	global_load_lds_dwordx4 v[220:221], off
	v_lshl_add_u64 v[220:221], s[86:87], 0, v[164:165]
	s_add_i32 m0, s40, 0xe000
	s_nop 0
	global_load_lds_dwordx4 v[220:221], off
	s_waitcnt vmcnt(8)
	s_waitcnt lgkmcnt(0)
	s_setprio 1
	s_barrier
	s_waitcnt lgkmcnt(0)
	v_mfma_f32_16x16x32_bf16 v[124:127], v[130:133], v[174:177], v[124:127]
	v_mfma_f32_16x16x32_bf16 v[120:123], v[138:141], v[174:177], v[120:123]
	v_mfma_f32_16x16x32_bf16 v[108:111], v[130:133], v[188:191], v[108:111]
	v_mfma_f32_16x16x32_bf16 v[104:107], v[138:141], v[188:191], v[104:107]
	v_mfma_f32_16x16x32_bf16 v[92:95], v[130:133], v[204:207], v[92:95]
	v_mfma_f32_16x16x32_bf16 v[88:91], v[138:141], v[204:207], v[88:91]
	v_mfma_f32_16x16x32_bf16 v[76:79], v[130:133], v[212:215], v[76:79]
	v_mfma_f32_16x16x32_bf16 v[72:75], v[138:141], v[212:215], v[72:75]
	v_mfma_f32_16x16x32_bf16 v[124:127], v[134:137], v[178:181], v[124:127]
	v_mfma_f32_16x16x32_bf16 v[120:123], v[142:145], v[178:181], v[120:123]
	v_mfma_f32_16x16x32_bf16 v[108:111], v[134:137], v[192:195], v[108:111]
	v_mfma_f32_16x16x32_bf16 v[104:107], v[142:145], v[192:195], v[104:107]
	v_mfma_f32_16x16x32_bf16 v[92:95], v[134:137], v[208:211], v[92:95]
	v_mfma_f32_16x16x32_bf16 v[88:91], v[142:145], v[208:211], v[88:91]
	v_mfma_f32_16x16x32_bf16 v[76:79], v[134:137], v[216:219], v[76:79]
	v_mfma_f32_16x16x32_bf16 v[72:75], v[142:145], v[216:219], v[72:75]
	v_mfma_f32_16x16x32_bf16 v[116:119], v[146:149], v[174:177], v[116:119]
	v_mfma_f32_16x16x32_bf16 v[112:115], v[166:169], v[174:177], v[112:115]
	v_mfma_f32_16x16x32_bf16 v[100:103], v[146:149], v[188:191], v[100:103]
	v_mfma_f32_16x16x32_bf16 v[96:99], v[166:169], v[188:191], v[96:99]
	v_mfma_f32_16x16x32_bf16 v[84:87], v[146:149], v[204:207], v[84:87]
	v_mfma_f32_16x16x32_bf16 v[80:83], v[166:169], v[204:207], v[80:83]
	v_mfma_f32_16x16x32_bf16 v[68:71], v[146:149], v[212:215], v[68:71]
	v_mfma_f32_16x16x32_bf16 v[64:67], v[166:169], v[212:215], v[64:67]
	v_mfma_f32_16x16x32_bf16 v[116:119], v[150:153], v[178:181], v[116:119]
	v_mfma_f32_16x16x32_bf16 v[112:115], v[170:173], v[178:181], v[112:115]
	v_mfma_f32_16x16x32_bf16 v[100:103], v[150:153], v[192:195], v[100:103]
	v_mfma_f32_16x16x32_bf16 v[96:99], v[170:173], v[192:195], v[96:99]
	v_mfma_f32_16x16x32_bf16 v[84:87], v[150:153], v[208:211], v[84:87]
	v_mfma_f32_16x16x32_bf16 v[80:83], v[170:173], v[208:211], v[80:83]
	v_mfma_f32_16x16x32_bf16 v[68:71], v[150:153], v[216:219], v[68:71]
	v_mfma_f32_16x16x32_bf16 v[64:67], v[170:173], v[216:219], v[64:67]
	s_barrier
	s_setprio 0
	s_add_i32 s58, s58, s69
	v_lshl_add_u64 v[220:221], s[44:45], 0, v[158:159]
	s_mov_b32 m0, s58
	ds_read_b128 v[174:177], v187 offset:16384
	ds_read_b128 v[178:181], v187 offset:17408
	ds_read_b128 v[188:191], v187 offset:18432
	ds_read_b128 v[192:195], v187 offset:19456
	ds_read_b128 v[204:207], v187 offset:20480
	ds_read_b128 v[208:211], v187 offset:21504
	ds_read_b128 v[212:215], v187 offset:22528
	ds_read_b128 v[216:219], v187 offset:23552
	global_load_lds_dwordx4 v[220:221], off
	s_add_i32 m0, s58, 0x2000
	v_lshl_add_u64 v[222:223], s[44:45], 0, v[154:155]
	s_add_u32 s44, s44, s70
	s_addc_u32 s45, s45, s71
	s_add_i32 s55, s55, s69
	global_load_lds_dwordx4 v[222:223], off
	v_lshl_add_u64 v[224:225], s[44:45], 0, v[158:159]
	s_mov_b32 m0, s55
	v_lshl_add_u64 v[226:227], s[44:45], 0, v[154:155]
	global_load_lds_dwordx4 v[224:225], off
	s_add_i32 m0, s55, 0x2000
	v_lshl_add_u64 v[228:229], s[88:89], 0, v[160:161]
	global_load_lds_dwordx4 v[226:227], off
	s_mov_b32 m0, s40
	v_lshl_add_u64 v[230:231], s[88:89], 0, v[156:157]
	global_load_lds_dwordx4 v[228:229], off
	s_mov_b32 m0, s4
	s_nop 0
	global_load_lds_dwordx4 v[230:231], off
	s_waitcnt vmcnt(8)
	s_waitcnt lgkmcnt(0)
	s_setprio 1
	s_barrier
	s_waitcnt lgkmcnt(0)
	v_mfma_f32_16x16x32_bf16 v[60:63], v[130:133], v[174:177], v[60:63]
	v_mfma_f32_16x16x32_bf16 v[56:59], v[138:141], v[174:177], v[56:59]
	v_mfma_f32_16x16x32_bf16 v[44:47], v[130:133], v[188:191], v[44:47]
	v_mfma_f32_16x16x32_bf16 v[40:43], v[138:141], v[188:191], v[40:43]
	v_mfma_f32_16x16x32_bf16 v[28:31], v[130:133], v[204:207], v[28:31]
	v_mfma_f32_16x16x32_bf16 v[24:27], v[138:141], v[204:207], v[24:27]
	v_mfma_f32_16x16x32_bf16 v[12:15], v[130:133], v[212:215], v[12:15]
	v_mfma_f32_16x16x32_bf16 v[8:11], v[138:141], v[212:215], v[8:11]
	v_mfma_f32_16x16x32_bf16 v[60:63], v[134:137], v[178:181], v[60:63]
	v_mfma_f32_16x16x32_bf16 v[56:59], v[142:145], v[178:181], v[56:59]
	v_mfma_f32_16x16x32_bf16 v[44:47], v[134:137], v[192:195], v[44:47]
	v_mfma_f32_16x16x32_bf16 v[40:43], v[142:145], v[192:195], v[40:43]
	v_mfma_f32_16x16x32_bf16 v[28:31], v[134:137], v[208:211], v[28:31]
	v_mfma_f32_16x16x32_bf16 v[24:27], v[142:145], v[208:211], v[24:27]
	v_mfma_f32_16x16x32_bf16 v[12:15], v[134:137], v[216:219], v[12:15]
	v_mfma_f32_16x16x32_bf16 v[8:11], v[142:145], v[216:219], v[8:11]
	v_mfma_f32_16x16x32_bf16 v[52:55], v[146:149], v[174:177], v[52:55]
	v_mfma_f32_16x16x32_bf16 v[48:51], v[166:169], v[174:177], v[48:51]
	v_mfma_f32_16x16x32_bf16 v[36:39], v[146:149], v[188:191], v[36:39]
	v_mfma_f32_16x16x32_bf16 v[32:35], v[166:169], v[188:191], v[32:35]
	v_mfma_f32_16x16x32_bf16 v[20:23], v[146:149], v[204:207], v[20:23]
	v_mfma_f32_16x16x32_bf16 v[16:19], v[166:169], v[204:207], v[16:19]
	v_mfma_f32_16x16x32_bf16 v[4:7], v[146:149], v[212:215], v[4:7]
	v_mfma_f32_16x16x32_bf16 v[0:3], v[166:169], v[212:215], v[0:3]
	v_mfma_f32_16x16x32_bf16 v[52:55], v[150:153], v[178:181], v[52:55]
	v_mfma_f32_16x16x32_bf16 v[48:51], v[170:173], v[178:181], v[48:51]
	v_mfma_f32_16x16x32_bf16 v[36:39], v[150:153], v[192:195], v[36:39]
	v_mfma_f32_16x16x32_bf16 v[32:35], v[170:173], v[192:195], v[32:35]
	v_mfma_f32_16x16x32_bf16 v[20:23], v[150:153], v[208:211], v[20:23]
	v_mfma_f32_16x16x32_bf16 v[16:19], v[170:173], v[208:211], v[16:19]
	v_mfma_f32_16x16x32_bf16 v[4:7], v[150:153], v[216:219], v[4:7]
	v_mfma_f32_16x16x32_bf16 v[0:3], v[170:173], v[216:219], v[0:3]
	s_barrier
	s_setprio 0
	s_add_i32 s55, 0, 0x18000
	v_add_u32_e32 v128, s55, v185
	s_add_i32 s58, 0, 0x1c000
	ds_read_b128 v[130:133], v128
	ds_read_b128 v[134:137], v128 offset:1024
	ds_read_b128 v[138:141], v128 offset:2048
	ds_read_b128 v[142:145], v128 offset:3072
	v_add_u32_e32 v128, s58, v185
	ds_read_b128 v[146:149], v128
	ds_read_b128 v[150:153], v128 offset:1024
	ds_read_b128 v[166:169], v128 offset:2048
	ds_read_b128 v[170:173], v128 offset:3072
	s_add_u32 s44, s88, s70
	s_addc_u32 s45, s89, s71
	s_mov_b32 m0, s5
	v_lshl_add_u64 v[232:233], s[44:45], 0, v[160:161]
	ds_read_b128 v[174:177], v187 offset:32768
	ds_read_b128 v[178:181], v187 offset:33792
	ds_read_b128 v[188:191], v187 offset:34816
	ds_read_b128 v[192:195], v187 offset:35840
	ds_read_b128 v[204:207], v187 offset:36864
	ds_read_b128 v[208:211], v187 offset:37888
	ds_read_b128 v[212:215], v187 offset:38912
	ds_read_b128 v[216:219], v187 offset:39936
	global_load_lds_dwordx4 v[232:233], off
	v_lshl_add_u64 v[232:233], s[44:45], 0, v[156:157]
	s_mov_b32 m0, s12
	s_nop 0
	global_load_lds_dwordx4 v[232:233], off
	s_waitcnt vmcnt(8)
	s_waitcnt lgkmcnt(0)
	s_setprio 1
	s_barrier
	s_waitcnt lgkmcnt(0)
	v_mfma_f32_16x16x32_bf16 v[124:127], v[130:133], v[174:177], v[124:127]
	v_mfma_f32_16x16x32_bf16 v[120:123], v[138:141], v[174:177], v[120:123]
	v_mfma_f32_16x16x32_bf16 v[108:111], v[130:133], v[188:191], v[108:111]
	v_mfma_f32_16x16x32_bf16 v[104:107], v[138:141], v[188:191], v[104:107]
	v_mfma_f32_16x16x32_bf16 v[92:95], v[130:133], v[204:207], v[92:95]
	v_mfma_f32_16x16x32_bf16 v[88:91], v[138:141], v[204:207], v[88:91]
	v_mfma_f32_16x16x32_bf16 v[76:79], v[130:133], v[212:215], v[76:79]
	v_mfma_f32_16x16x32_bf16 v[72:75], v[138:141], v[212:215], v[72:75]
	v_mfma_f32_16x16x32_bf16 v[124:127], v[134:137], v[178:181], v[124:127]
	v_mfma_f32_16x16x32_bf16 v[120:123], v[142:145], v[178:181], v[120:123]
	v_mfma_f32_16x16x32_bf16 v[108:111], v[134:137], v[192:195], v[108:111]
	v_mfma_f32_16x16x32_bf16 v[104:107], v[142:145], v[192:195], v[104:107]
	v_mfma_f32_16x16x32_bf16 v[92:95], v[134:137], v[208:211], v[92:95]
	v_mfma_f32_16x16x32_bf16 v[88:91], v[142:145], v[208:211], v[88:91]
	v_mfma_f32_16x16x32_bf16 v[76:79], v[134:137], v[216:219], v[76:79]
	v_mfma_f32_16x16x32_bf16 v[72:75], v[142:145], v[216:219], v[72:75]
	v_mfma_f32_16x16x32_bf16 v[116:119], v[146:149], v[174:177], v[116:119]
	v_mfma_f32_16x16x32_bf16 v[112:115], v[166:169], v[174:177], v[112:115]
	v_mfma_f32_16x16x32_bf16 v[100:103], v[146:149], v[188:191], v[100:103]
	v_mfma_f32_16x16x32_bf16 v[96:99], v[166:169], v[188:191], v[96:99]
	v_mfma_f32_16x16x32_bf16 v[84:87], v[146:149], v[204:207], v[84:87]
	v_mfma_f32_16x16x32_bf16 v[80:83], v[166:169], v[204:207], v[80:83]
	v_mfma_f32_16x16x32_bf16 v[68:71], v[146:149], v[212:215], v[68:71]
	v_mfma_f32_16x16x32_bf16 v[64:67], v[166:169], v[212:215], v[64:67]
	v_mfma_f32_16x16x32_bf16 v[116:119], v[150:153], v[178:181], v[116:119]
	v_mfma_f32_16x16x32_bf16 v[112:115], v[170:173], v[178:181], v[112:115]
	v_mfma_f32_16x16x32_bf16 v[100:103], v[150:153], v[192:195], v[100:103]
	v_mfma_f32_16x16x32_bf16 v[96:99], v[170:173], v[192:195], v[96:99]
	v_mfma_f32_16x16x32_bf16 v[84:87], v[150:153], v[208:211], v[84:87]
	v_mfma_f32_16x16x32_bf16 v[80:83], v[170:173], v[208:211], v[80:83]
	v_mfma_f32_16x16x32_bf16 v[68:71], v[150:153], v[216:219], v[68:71]
	v_mfma_f32_16x16x32_bf16 v[64:67], v[170:173], v[216:219], v[64:67]
	s_barrier
	s_setprio 0
	s_add_i32 s44, s55, s69
	v_lshl_add_u64 v[220:221], v[220:221], 0, s[52:53]
	s_mov_b32 m0, s44
	ds_read_b128 v[174:177], v187 offset:49152
	ds_read_b128 v[178:181], v187 offset:50176
	ds_read_b128 v[188:191], v187 offset:51200
	ds_read_b128 v[192:195], v187 offset:52224
	ds_read_b128 v[204:207], v187 offset:53248
	ds_read_b128 v[208:211], v187 offset:54272
	ds_read_b128 v[212:215], v187 offset:55296
	ds_read_b128 v[216:219], v187 offset:56320
	global_load_lds_dwordx4 v[220:221], off
	v_lshl_add_u64 v[220:221], v[222:223], 0, s[52:53]
	s_add_i32 m0, s44, 0x2000
	s_add_i32 s44, s58, s69
	global_load_lds_dwordx4 v[220:221], off
	v_lshl_add_u64 v[220:221], v[224:225], 0, s[52:53]
	s_mov_b32 m0, s44
	s_nop 0
	global_load_lds_dwordx4 v[220:221], off
	v_lshl_add_u64 v[220:221], v[226:227], 0, s[52:53]
	s_add_i32 m0, s44, 0x2000
	s_nop 0
	global_load_lds_dwordx4 v[220:221], off
	v_lshl_add_u64 v[220:221], v[228:229], 0, s[52:53]
	s_mov_b32 m0, s22
	s_nop 0
	global_load_lds_dwordx4 v[220:221], off
	v_lshl_add_u64 v[220:221], v[230:231], 0, s[52:53]
	s_mov_b32 m0, s23
	s_nop 0
	global_load_lds_dwordx4 v[220:221], off
	s_waitcnt vmcnt(8)
	s_waitcnt lgkmcnt(0)
	s_setprio 1
	s_barrier
	s_waitcnt lgkmcnt(0)
	v_mfma_f32_16x16x32_bf16 v[60:63], v[130:133], v[174:177], v[60:63]
	v_mfma_f32_16x16x32_bf16 v[56:59], v[138:141], v[174:177], v[56:59]
	v_mfma_f32_16x16x32_bf16 v[44:47], v[130:133], v[188:191], v[44:47]
	v_mfma_f32_16x16x32_bf16 v[40:43], v[138:141], v[188:191], v[40:43]
	v_mfma_f32_16x16x32_bf16 v[28:31], v[130:133], v[204:207], v[28:31]
	v_mfma_f32_16x16x32_bf16 v[24:27], v[138:141], v[204:207], v[24:27]
	v_mfma_f32_16x16x32_bf16 v[12:15], v[130:133], v[212:215], v[12:15]
	v_mfma_f32_16x16x32_bf16 v[8:11], v[138:141], v[212:215], v[8:11]
	v_mfma_f32_16x16x32_bf16 v[60:63], v[134:137], v[178:181], v[60:63]
	v_mfma_f32_16x16x32_bf16 v[56:59], v[142:145], v[178:181], v[56:59]
	v_mfma_f32_16x16x32_bf16 v[44:47], v[134:137], v[192:195], v[44:47]
	v_mfma_f32_16x16x32_bf16 v[40:43], v[142:145], v[192:195], v[40:43]
	v_mfma_f32_16x16x32_bf16 v[28:31], v[134:137], v[208:211], v[28:31]
	v_mfma_f32_16x16x32_bf16 v[24:27], v[142:145], v[208:211], v[24:27]
	v_mfma_f32_16x16x32_bf16 v[12:15], v[134:137], v[216:219], v[12:15]
	v_mfma_f32_16x16x32_bf16 v[8:11], v[142:145], v[216:219], v[8:11]
	v_mfma_f32_16x16x32_bf16 v[52:55], v[146:149], v[174:177], v[52:55]
	v_mfma_f32_16x16x32_bf16 v[48:51], v[166:169], v[174:177], v[48:51]
	v_mfma_f32_16x16x32_bf16 v[36:39], v[146:149], v[188:191], v[36:39]
	v_mfma_f32_16x16x32_bf16 v[32:35], v[166:169], v[188:191], v[32:35]
	v_mfma_f32_16x16x32_bf16 v[20:23], v[146:149], v[204:207], v[20:23]
	v_mfma_f32_16x16x32_bf16 v[16:19], v[166:169], v[204:207], v[16:19]
	v_mfma_f32_16x16x32_bf16 v[4:7], v[146:149], v[212:215], v[4:7]
	v_mfma_f32_16x16x32_bf16 v[0:3], v[166:169], v[212:215], v[0:3]
	v_mfma_f32_16x16x32_bf16 v[52:55], v[150:153], v[178:181], v[52:55]
	v_mfma_f32_16x16x32_bf16 v[48:51], v[170:173], v[178:181], v[48:51]
	v_mfma_f32_16x16x32_bf16 v[36:39], v[150:153], v[192:195], v[36:39]
	v_mfma_f32_16x16x32_bf16 v[32:35], v[170:173], v[192:195], v[32:35]
	v_mfma_f32_16x16x32_bf16 v[20:23], v[150:153], v[208:211], v[20:23]
	v_mfma_f32_16x16x32_bf16 v[16:19], v[170:173], v[208:211], v[16:19]
	v_mfma_f32_16x16x32_bf16 v[4:7], v[150:153], v[216:219], v[4:7]
	v_mfma_f32_16x16x32_bf16 v[0:3], v[170:173], v[216:219], v[0:3]
	s_barrier
	s_setprio 0
	s_add_u32 s86, s86, 0x100
	s_addc_u32 s87, s87, 0
	s_add_u32 s16, s16, 0x100
	s_addc_u32 s54, s54, 0
	s_cmp_ge_i32 s65, s13
	s_mov_b32 s55, s65
	s_cbranch_scc0 .LBB0_1122

.LBB0_1165:
	s_add_i32 s84, s82, 2
	s_add_u32 s44, s80, 0x80
	s_addc_u32 s45, s81, 0
	s_add_i32 s58, 0, 0x10000
	s_cmp_eq_u32 s41, s82
	s_cselect_b32 s83, s11, s45
	s_cselect_b32 s82, s10, s44
	v_add_u32_e32 v128, s58, v185
	s_cselect_b32 s45, s79, s55
	s_cselect_b32 s44, s78, s16
	s_add_i32 s85, 0, 0x14000
	ds_read_b128 v[130:133], v128
	ds_read_b128 v[134:137], v128 offset:1024
	ds_read_b128 v[138:141], v128 offset:2048
	ds_read_b128 v[142:145], v128 offset:3072
	v_add_u32_e32 v128, s85, v185
	ds_read_b128 v[146:149], v128
	ds_read_b128 v[150:153], v128 offset:1024
	ds_read_b128 v[166:169], v128 offset:2048
	ds_read_b128 v[170:173], v128 offset:3072
	v_lshl_add_u64 v[220:221], s[80:81], 0, v[162:163]
	s_add_i32 m0, s4, 0xc000
	ds_read_b128 v[174:177], v187
	ds_read_b128 v[178:181], v187 offset:1024
	ds_read_b128 v[188:191], v187 offset:2048
	ds_read_b128 v[192:195], v187 offset:3072
	ds_read_b128 v[204:207], v187 offset:4096
	ds_read_b128 v[208:211], v187 offset:5120
	ds_read_b128 v[212:215], v187 offset:6144
	ds_read_b128 v[216:219], v187 offset:7168
	global_load_lds_dwordx4 v[220:221], off
	v_lshl_add_u64 v[220:221], s[80:81], 0, v[164:165]
	s_add_i32 m0, s4, 0xe000
	s_nop 0
	global_load_lds_dwordx4 v[220:221], off
	s_waitcnt vmcnt(8)
	s_waitcnt lgkmcnt(0)
	s_setprio 1
	s_barrier
	s_waitcnt lgkmcnt(0)
	v_mfma_f32_16x16x32_bf16 v[124:127], v[130:133], v[174:177], v[124:127]
	v_mfma_f32_16x16x32_bf16 v[120:123], v[138:141], v[174:177], v[120:123]
	v_mfma_f32_16x16x32_bf16 v[108:111], v[130:133], v[188:191], v[108:111]
	v_mfma_f32_16x16x32_bf16 v[104:107], v[138:141], v[188:191], v[104:107]
	v_mfma_f32_16x16x32_bf16 v[92:95], v[130:133], v[204:207], v[92:95]
	v_mfma_f32_16x16x32_bf16 v[88:91], v[138:141], v[204:207], v[88:91]
	v_mfma_f32_16x16x32_bf16 v[76:79], v[130:133], v[212:215], v[76:79]
	v_mfma_f32_16x16x32_bf16 v[72:75], v[138:141], v[212:215], v[72:75]
	v_mfma_f32_16x16x32_bf16 v[124:127], v[134:137], v[178:181], v[124:127]
	v_mfma_f32_16x16x32_bf16 v[120:123], v[142:145], v[178:181], v[120:123]
	v_mfma_f32_16x16x32_bf16 v[108:111], v[134:137], v[192:195], v[108:111]
	v_mfma_f32_16x16x32_bf16 v[104:107], v[142:145], v[192:195], v[104:107]
	v_mfma_f32_16x16x32_bf16 v[92:95], v[134:137], v[208:211], v[92:95]
	v_mfma_f32_16x16x32_bf16 v[88:91], v[142:145], v[208:211], v[88:91]
	v_mfma_f32_16x16x32_bf16 v[76:79], v[134:137], v[216:219], v[76:79]
	v_mfma_f32_16x16x32_bf16 v[72:75], v[142:145], v[216:219], v[72:75]
	v_mfma_f32_16x16x32_bf16 v[116:119], v[146:149], v[174:177], v[116:119]
	v_mfma_f32_16x16x32_bf16 v[112:115], v[166:169], v[174:177], v[112:115]
	v_mfma_f32_16x16x32_bf16 v[100:103], v[146:149], v[188:191], v[100:103]
	v_mfma_f32_16x16x32_bf16 v[96:99], v[166:169], v[188:191], v[96:99]
	v_mfma_f32_16x16x32_bf16 v[84:87], v[146:149], v[204:207], v[84:87]
	v_mfma_f32_16x16x32_bf16 v[80:83], v[166:169], v[204:207], v[80:83]
	v_mfma_f32_16x16x32_bf16 v[68:71], v[146:149], v[212:215], v[68:71]
	v_mfma_f32_16x16x32_bf16 v[64:67], v[166:169], v[212:215], v[64:67]
	v_mfma_f32_16x16x32_bf16 v[116:119], v[150:153], v[178:181], v[116:119]
	v_mfma_f32_16x16x32_bf16 v[112:115], v[170:173], v[178:181], v[112:115]
	v_mfma_f32_16x16x32_bf16 v[100:103], v[150:153], v[192:195], v[100:103]
	v_mfma_f32_16x16x32_bf16 v[96:99], v[170:173], v[192:195], v[96:99]
	v_mfma_f32_16x16x32_bf16 v[84:87], v[150:153], v[208:211], v[84:87]
	v_mfma_f32_16x16x32_bf16 v[80:83], v[170:173], v[208:211], v[80:83]
	v_mfma_f32_16x16x32_bf16 v[68:71], v[150:153], v[216:219], v[68:71]
	v_mfma_f32_16x16x32_bf16 v[64:67], v[170:173], v[216:219], v[64:67]
	s_barrier
	s_setprio 0
	s_add_i32 s58, s58, s40
	v_lshl_add_u64 v[220:221], s[44:45], 0, v[158:159]
	s_mov_b32 m0, s58
	ds_read_b128 v[174:177], v187 offset:16384
	ds_read_b128 v[178:181], v187 offset:17408
	ds_read_b128 v[188:191], v187 offset:18432
	ds_read_b128 v[192:195], v187 offset:19456
	ds_read_b128 v[204:207], v187 offset:20480
	ds_read_b128 v[208:211], v187 offset:21504
	ds_read_b128 v[212:215], v187 offset:22528
	ds_read_b128 v[216:219], v187 offset:23552
	global_load_lds_dwordx4 v[220:221], off
	s_add_i32 m0, s58, 0x2000
	v_lshl_add_u64 v[222:223], s[44:45], 0, v[154:155]
	s_add_u32 s44, s44, s70
	s_addc_u32 s45, s45, s71
	s_add_i32 s58, s85, s40
	global_load_lds_dwordx4 v[222:223], off
	v_lshl_add_u64 v[224:225], s[44:45], 0, v[158:159]
	s_mov_b32 m0, s58
	v_lshl_add_u64 v[226:227], s[44:45], 0, v[154:155]
	global_load_lds_dwordx4 v[224:225], off
	s_add_i32 m0, s58, 0x2000
	v_lshl_add_u64 v[228:229], s[82:83], 0, v[160:161]
	global_load_lds_dwordx4 v[226:227], off
	s_mov_b32 m0, s4
	v_lshl_add_u64 v[230:231], s[82:83], 0, v[156:157]
	global_load_lds_dwordx4 v[228:229], off
	s_mov_b32 m0, s5
	s_nop 0
	global_load_lds_dwordx4 v[230:231], off
	s_waitcnt vmcnt(8)
	s_waitcnt lgkmcnt(0)
	s_setprio 1
	s_barrier
	s_waitcnt lgkmcnt(0)
	v_mfma_f32_16x16x32_bf16 v[60:63], v[130:133], v[174:177], v[60:63]
	v_mfma_f32_16x16x32_bf16 v[56:59], v[138:141], v[174:177], v[56:59]
	v_mfma_f32_16x16x32_bf16 v[44:47], v[130:133], v[188:191], v[44:47]
	v_mfma_f32_16x16x32_bf16 v[40:43], v[138:141], v[188:191], v[40:43]
	v_mfma_f32_16x16x32_bf16 v[28:31], v[130:133], v[204:207], v[28:31]
	v_mfma_f32_16x16x32_bf16 v[24:27], v[138:141], v[204:207], v[24:27]
	v_mfma_f32_16x16x32_bf16 v[12:15], v[130:133], v[212:215], v[12:15]
	v_mfma_f32_16x16x32_bf16 v[8:11], v[138:141], v[212:215], v[8:11]
	v_mfma_f32_16x16x32_bf16 v[60:63], v[134:137], v[178:181], v[60:63]
	v_mfma_f32_16x16x32_bf16 v[56:59], v[142:145], v[178:181], v[56:59]
	v_mfma_f32_16x16x32_bf16 v[44:47], v[134:137], v[192:195], v[44:47]
	v_mfma_f32_16x16x32_bf16 v[40:43], v[142:145], v[192:195], v[40:43]
	v_mfma_f32_16x16x32_bf16 v[28:31], v[134:137], v[208:211], v[28:31]
	v_mfma_f32_16x16x32_bf16 v[24:27], v[142:145], v[208:211], v[24:27]
	v_mfma_f32_16x16x32_bf16 v[12:15], v[134:137], v[216:219], v[12:15]
	v_mfma_f32_16x16x32_bf16 v[8:11], v[142:145], v[216:219], v[8:11]
	v_mfma_f32_16x16x32_bf16 v[52:55], v[146:149], v[174:177], v[52:55]
	v_mfma_f32_16x16x32_bf16 v[48:51], v[166:169], v[174:177], v[48:51]
	v_mfma_f32_16x16x32_bf16 v[36:39], v[146:149], v[188:191], v[36:39]
	v_mfma_f32_16x16x32_bf16 v[32:35], v[166:169], v[188:191], v[32:35]
	v_mfma_f32_16x16x32_bf16 v[20:23], v[146:149], v[204:207], v[20:23]
	v_mfma_f32_16x16x32_bf16 v[16:19], v[166:169], v[204:207], v[16:19]
	v_mfma_f32_16x16x32_bf16 v[4:7], v[146:149], v[212:215], v[4:7]
	v_mfma_f32_16x16x32_bf16 v[0:3], v[166:169], v[212:215], v[0:3]
	v_mfma_f32_16x16x32_bf16 v[52:55], v[150:153], v[178:181], v[52:55]
	v_mfma_f32_16x16x32_bf16 v[48:51], v[170:173], v[178:181], v[48:51]
	v_mfma_f32_16x16x32_bf16 v[36:39], v[150:153], v[192:195], v[36:39]
	v_mfma_f32_16x16x32_bf16 v[32:35], v[170:173], v[192:195], v[32:35]
	v_mfma_f32_16x16x32_bf16 v[20:23], v[150:153], v[208:211], v[20:23]
	v_mfma_f32_16x16x32_bf16 v[16:19], v[170:173], v[208:211], v[16:19]
	v_mfma_f32_16x16x32_bf16 v[4:7], v[150:153], v[216:219], v[4:7]
	v_mfma_f32_16x16x32_bf16 v[0:3], v[170:173], v[216:219], v[0:3]
	s_barrier
	s_setprio 0
	s_add_i32 s58, 0, 0x18000
	v_add_u32_e32 v128, s58, v185
	s_add_i32 s85, 0, 0x1c000
	ds_read_b128 v[130:133], v128
	ds_read_b128 v[134:137], v128 offset:1024
	ds_read_b128 v[138:141], v128 offset:2048
	ds_read_b128 v[142:145], v128 offset:3072
	v_add_u32_e32 v128, s85, v185
	ds_read_b128 v[146:149], v128
	ds_read_b128 v[150:153], v128 offset:1024
	ds_read_b128 v[166:169], v128 offset:2048
	ds_read_b128 v[170:173], v128 offset:3072
	s_add_u32 s44, s82, s70
	s_addc_u32 s45, s83, s71
	s_mov_b32 m0, s12
	v_lshl_add_u64 v[232:233], s[44:45], 0, v[160:161]
	ds_read_b128 v[174:177], v187 offset:32768
	ds_read_b128 v[178:181], v187 offset:33792
	ds_read_b128 v[188:191], v187 offset:34816
	ds_read_b128 v[192:195], v187 offset:35840
	ds_read_b128 v[204:207], v187 offset:36864
	ds_read_b128 v[208:211], v187 offset:37888
	ds_read_b128 v[212:215], v187 offset:38912
	ds_read_b128 v[216:219], v187 offset:39936
	global_load_lds_dwordx4 v[232:233], off
	v_lshl_add_u64 v[232:233], s[44:45], 0, v[156:157]
	s_mov_b32 m0, s13
	s_nop 0
	global_load_lds_dwordx4 v[232:233], off
	s_waitcnt vmcnt(8)
	s_waitcnt lgkmcnt(0)
	s_setprio 1
	s_barrier
	s_waitcnt lgkmcnt(0)
	v_mfma_f32_16x16x32_bf16 v[124:127], v[130:133], v[174:177], v[124:127]
	v_mfma_f32_16x16x32_bf16 v[120:123], v[138:141], v[174:177], v[120:123]
	v_mfma_f32_16x16x32_bf16 v[108:111], v[130:133], v[188:191], v[108:111]
	v_mfma_f32_16x16x32_bf16 v[104:107], v[138:141], v[188:191], v[104:107]
	v_mfma_f32_16x16x32_bf16 v[92:95], v[130:133], v[204:207], v[92:95]
	v_mfma_f32_16x16x32_bf16 v[88:91], v[138:141], v[204:207], v[88:91]
	v_mfma_f32_16x16x32_bf16 v[76:79], v[130:133], v[212:215], v[76:79]
	v_mfma_f32_16x16x32_bf16 v[72:75], v[138:141], v[212:215], v[72:75]
	v_mfma_f32_16x16x32_bf16 v[124:127], v[134:137], v[178:181], v[124:127]
	v_mfma_f32_16x16x32_bf16 v[120:123], v[142:145], v[178:181], v[120:123]
	v_mfma_f32_16x16x32_bf16 v[108:111], v[134:137], v[192:195], v[108:111]
	v_mfma_f32_16x16x32_bf16 v[104:107], v[142:145], v[192:195], v[104:107]
	v_mfma_f32_16x16x32_bf16 v[92:95], v[134:137], v[208:211], v[92:95]
	v_mfma_f32_16x16x32_bf16 v[88:91], v[142:145], v[208:211], v[88:91]
	v_mfma_f32_16x16x32_bf16 v[76:79], v[134:137], v[216:219], v[76:79]
	v_mfma_f32_16x16x32_bf16 v[72:75], v[142:145], v[216:219], v[72:75]
	v_mfma_f32_16x16x32_bf16 v[116:119], v[146:149], v[174:177], v[116:119]
	v_mfma_f32_16x16x32_bf16 v[112:115], v[166:169], v[174:177], v[112:115]
	v_mfma_f32_16x16x32_bf16 v[100:103], v[146:149], v[188:191], v[100:103]
	v_mfma_f32_16x16x32_bf16 v[96:99], v[166:169], v[188:191], v[96:99]
	v_mfma_f32_16x16x32_bf16 v[84:87], v[146:149], v[204:207], v[84:87]
	v_mfma_f32_16x16x32_bf16 v[80:83], v[166:169], v[204:207], v[80:83]
	v_mfma_f32_16x16x32_bf16 v[68:71], v[146:149], v[212:215], v[68:71]
	v_mfma_f32_16x16x32_bf16 v[64:67], v[166:169], v[212:215], v[64:67]
	v_mfma_f32_16x16x32_bf16 v[116:119], v[150:153], v[178:181], v[116:119]
	v_mfma_f32_16x16x32_bf16 v[112:115], v[170:173], v[178:181], v[112:115]
	v_mfma_f32_16x16x32_bf16 v[100:103], v[150:153], v[192:195], v[100:103]
	v_mfma_f32_16x16x32_bf16 v[96:99], v[170:173], v[192:195], v[96:99]
	v_mfma_f32_16x16x32_bf16 v[84:87], v[150:153], v[208:211], v[84:87]
	v_mfma_f32_16x16x32_bf16 v[80:83], v[170:173], v[208:211], v[80:83]
	v_mfma_f32_16x16x32_bf16 v[68:71], v[150:153], v[216:219], v[68:71]
	v_mfma_f32_16x16x32_bf16 v[64:67], v[170:173], v[216:219], v[64:67]
	s_barrier
	s_setprio 0
	s_add_i32 s44, s58, s40
	v_lshl_add_u64 v[220:221], v[220:221], 0, s[52:53]
	s_mov_b32 m0, s44
	ds_read_b128 v[174:177], v187 offset:49152
	ds_read_b128 v[178:181], v187 offset:50176
	ds_read_b128 v[188:191], v187 offset:51200
	ds_read_b128 v[192:195], v187 offset:52224
	ds_read_b128 v[204:207], v187 offset:53248
	ds_read_b128 v[208:211], v187 offset:54272
	ds_read_b128 v[212:215], v187 offset:55296
	ds_read_b128 v[216:219], v187 offset:56320
	global_load_lds_dwordx4 v[220:221], off
	v_lshl_add_u64 v[220:221], v[222:223], 0, s[52:53]
	s_add_i32 m0, s44, 0x2000
	s_add_i32 s44, s85, s40
	global_load_lds_dwordx4 v[220:221], off
	v_lshl_add_u64 v[220:221], v[224:225], 0, s[52:53]
	s_mov_b32 m0, s44
	s_nop 0
	global_load_lds_dwordx4 v[220:221], off
	v_lshl_add_u64 v[220:221], v[226:227], 0, s[52:53]
	s_add_i32 m0, s44, 0x2000
	s_nop 0
	global_load_lds_dwordx4 v[220:221], off
	v_lshl_add_u64 v[220:221], v[228:229], 0, s[52:53]
	s_mov_b32 m0, s23
	s_nop 0
	global_load_lds_dwordx4 v[220:221], off
	v_lshl_add_u64 v[220:221], v[230:231], 0, s[52:53]
	s_mov_b32 m0, s29
	s_nop 0
	global_load_lds_dwordx4 v[220:221], off
	s_waitcnt vmcnt(8)
	s_waitcnt lgkmcnt(0)
	s_setprio 1
	s_barrier
	s_waitcnt lgkmcnt(0)
	v_mfma_f32_16x16x32_bf16 v[60:63], v[130:133], v[174:177], v[60:63]
	v_mfma_f32_16x16x32_bf16 v[56:59], v[138:141], v[174:177], v[56:59]
	v_mfma_f32_16x16x32_bf16 v[44:47], v[130:133], v[188:191], v[44:47]
	v_mfma_f32_16x16x32_bf16 v[40:43], v[138:141], v[188:191], v[40:43]
	v_mfma_f32_16x16x32_bf16 v[28:31], v[130:133], v[204:207], v[28:31]
	v_mfma_f32_16x16x32_bf16 v[24:27], v[138:141], v[204:207], v[24:27]
	v_mfma_f32_16x16x32_bf16 v[12:15], v[130:133], v[212:215], v[12:15]
	v_mfma_f32_16x16x32_bf16 v[8:11], v[138:141], v[212:215], v[8:11]
	v_mfma_f32_16x16x32_bf16 v[60:63], v[134:137], v[178:181], v[60:63]
	v_mfma_f32_16x16x32_bf16 v[56:59], v[142:145], v[178:181], v[56:59]
	v_mfma_f32_16x16x32_bf16 v[44:47], v[134:137], v[192:195], v[44:47]
	v_mfma_f32_16x16x32_bf16 v[40:43], v[142:145], v[192:195], v[40:43]
	v_mfma_f32_16x16x32_bf16 v[28:31], v[134:137], v[208:211], v[28:31]
	v_mfma_f32_16x16x32_bf16 v[24:27], v[142:145], v[208:211], v[24:27]
	v_mfma_f32_16x16x32_bf16 v[12:15], v[134:137], v[216:219], v[12:15]
	v_mfma_f32_16x16x32_bf16 v[8:11], v[142:145], v[216:219], v[8:11]
	v_mfma_f32_16x16x32_bf16 v[52:55], v[146:149], v[174:177], v[52:55]
	v_mfma_f32_16x16x32_bf16 v[48:51], v[166:169], v[174:177], v[48:51]
	v_mfma_f32_16x16x32_bf16 v[36:39], v[146:149], v[188:191], v[36:39]
	v_mfma_f32_16x16x32_bf16 v[32:35], v[166:169], v[188:191], v[32:35]
	v_mfma_f32_16x16x32_bf16 v[20:23], v[146:149], v[204:207], v[20:23]
	v_mfma_f32_16x16x32_bf16 v[16:19], v[166:169], v[204:207], v[16:19]
	v_mfma_f32_16x16x32_bf16 v[4:7], v[146:149], v[212:215], v[4:7]
	v_mfma_f32_16x16x32_bf16 v[0:3], v[166:169], v[212:215], v[0:3]
	v_mfma_f32_16x16x32_bf16 v[52:55], v[150:153], v[178:181], v[52:55]
	v_mfma_f32_16x16x32_bf16 v[48:51], v[170:173], v[178:181], v[48:51]
	v_mfma_f32_16x16x32_bf16 v[36:39], v[150:153], v[192:195], v[36:39]
	v_mfma_f32_16x16x32_bf16 v[32:35], v[170:173], v[192:195], v[32:35]
	v_mfma_f32_16x16x32_bf16 v[20:23], v[150:153], v[208:211], v[20:23]
	v_mfma_f32_16x16x32_bf16 v[16:19], v[170:173], v[208:211], v[16:19]
	v_mfma_f32_16x16x32_bf16 v[4:7], v[150:153], v[216:219], v[4:7]
	v_mfma_f32_16x16x32_bf16 v[0:3], v[170:173], v[216:219], v[0:3]
	s_barrier
	s_setprio 0
	s_add_u32 s80, s80, 0x100
	s_addc_u32 s81, s81, 0
	s_add_u32 s16, s16, 0x100
	s_addc_u32 s55, s55, 0
	s_cmp_ge_i32 s84, s22
	s_mov_b32 s82, s84
	s_cbranch_scc0 .LBB0_1165
